# P0 weight transposes rewritten by hand: scalar tile decode, source tiles of the next three rounds in flight with counted vmcnt waits
# speedup vs baseline: 1.0077x; 1.0018x over previous
.LBB0_245:
	v_and_b32_e32 v64, 63, v182
	v_lshrrev_b32_e32 v65, 6, v182
	v_lshrrev_b32_e32 v66, 3, v182
	v_and_b32_e32 v67, 7, v182
	v_lshlrev_b32_e32 v67, 3, v67
	v_mul_u32_u24_e32 v68, 0x41, v65
	v_add_lshl_u32 v68, v68, v64, 2
	v_add_u32_e32 v68, 0x8000, v68
	v_mul_u32_u24_e32 v69, 0x41, v67
	v_add_lshl_u32 v69, v69, v66, 2
	v_add_u32_e32 v69, 0x8000, v69
	s_mov_b32 s22, 0x223e3c3a
	s_mov_b32 s23, 0x1e022624
	s_mov_b32 s4, s2
	s_mov_b32 s5, 0
	s_cmp_ge_u32 s4, 0x2c0
	s_addc_u32 s5, s5, 0
	s_cmp_ge_u32 s4, 0x580
	s_addc_u32 s5, s5, 0
	s_cmp_ge_u32 s4, 0x840
	s_addc_u32 s5, s5, 0
	s_cmp_ge_u32 s4, 0xb00
	s_addc_u32 s5, s5, 0
	s_cmp_ge_u32 s4, 0xdc0
	s_addc_u32 s5, s5, 0
	s_cmp_ge_u32 s4, 0x1080
	s_addc_u32 s5, s5, 0
	s_cmp_ge_u32 s4, 0x13c0
	s_addc_u32 s5, s5, 0
	s_mul_i32 s12, s5, 0x2c0
	s_cmp_eq_u32 s5, 7
	s_cselect_b32 s13, 0x80, 0
	s_add_i32 s12, s12, s13
	s_sub_i32 s6, s4, s12
	s_cmp_eq_u32 s5, 2
	s_cselect_b32 s14, 1, 0
	s_cmp_eq_u32 s5, 5
	s_cselect_b32 s14, 1, s14
	s_mul_i32 s12, s6, 0x5d2
	s_lshr_b32 s12, s12, 16
	s_mul_i32 s15, s12, 44
	s_sub_i32 s15, s6, s15
	s_lshr_b32 s13, s6, 4
	s_and_b32 s8, s6, 15
	s_cmp_eq_u32 s14, 1
	s_cselect_b32 s7, s12, s13
	s_cselect_b32 s8, s15, s8
	s_movk_i32 s10, 0x400
	s_cselect_b32 s10, 0xb00, s10
	s_movk_i32 s9, 0xb00
	s_cselect_b32 s9, 0x400, s9
	s_cmp_eq_u32 s5, 7
	s_cselect_b32 s9, 0x400, s9
	s_cmp_eq_u32 s5, 6
	s_cselect_b32 s9, 0xd00, s9
	s_lshl_b32 s12, s5, 3
	s_lshr_b64 s[12:13], s[22:23], s12
	s_and_b32 s12, s12, 0xff
	s_add_i32 s13, s12, 1
	v_readlane_b32 s16, v241, s12
	v_readlane_b32 s17, v241, s13
	v_mul_u32_u24_e32 v70, s9, v65
	s_mul_i32 s14, s8, s9
	s_add_i32 s14, s14, s7
	s_lshl_b32 s14, s14, 8
	v_add_lshl_u32 v70, v70, v64, 2
	s_add_u32 s18, s16, s14
	s_addc_u32 s19, s17, 0
	s_lshl_b32 s15, s9, 5
	global_load_dword v72, v70, s[18:19]
	s_add_u32 s18, s18, s15
	s_addc_u32 s19, s19, 0
	global_load_dword v73, v70, s[18:19]
	s_add_u32 s18, s18, s15
	s_addc_u32 s19, s19, 0
	global_load_dword v74, v70, s[18:19]
	s_add_u32 s18, s18, s15
	s_addc_u32 s19, s19, 0
	global_load_dword v75, v70, s[18:19]
	s_add_u32 s18, s18, s15
	s_addc_u32 s19, s19, 0
	global_load_dword v76, v70, s[18:19]
	s_add_u32 s18, s18, s15
	s_addc_u32 s19, s19, 0
	global_load_dword v77, v70, s[18:19]
	s_add_u32 s18, s18, s15
	s_addc_u32 s19, s19, 0
	global_load_dword v78, v70, s[18:19]
	s_add_u32 s18, s18, s15
	s_addc_u32 s19, s19, 0
	global_load_dword v79, v70, s[18:19]
	s_add_i32 s4, s2, 0x100
	s_mov_b32 s5, 0
	s_cmp_ge_u32 s4, 0x2c0
	s_addc_u32 s5, s5, 0
	s_cmp_ge_u32 s4, 0x580
	s_addc_u32 s5, s5, 0
	s_cmp_ge_u32 s4, 0x840
	s_addc_u32 s5, s5, 0
	s_cmp_ge_u32 s4, 0xb00
	s_addc_u32 s5, s5, 0
	s_cmp_ge_u32 s4, 0xdc0
	s_addc_u32 s5, s5, 0
	s_cmp_ge_u32 s4, 0x1080
	s_addc_u32 s5, s5, 0
	s_cmp_ge_u32 s4, 0x13c0
	s_addc_u32 s5, s5, 0
	s_mul_i32 s12, s5, 0x2c0
	s_cmp_eq_u32 s5, 7
	s_cselect_b32 s13, 0x80, 0
	s_add_i32 s12, s12, s13
	s_sub_i32 s6, s4, s12
	s_cmp_eq_u32 s5, 2
	s_cselect_b32 s14, 1, 0
	s_cmp_eq_u32 s5, 5
	s_cselect_b32 s14, 1, s14
	s_mul_i32 s12, s6, 0x5d2
	s_lshr_b32 s12, s12, 16
	s_mul_i32 s15, s12, 44
	s_sub_i32 s15, s6, s15
	s_lshr_b32 s13, s6, 4
	s_and_b32 s8, s6, 15
	s_cmp_eq_u32 s14, 1
	s_cselect_b32 s7, s12, s13
	s_cselect_b32 s8, s15, s8
	s_movk_i32 s10, 0x400
	s_cselect_b32 s10, 0xb00, s10
	s_movk_i32 s9, 0xb00
	s_cselect_b32 s9, 0x400, s9
	s_cmp_eq_u32 s5, 7
	s_cselect_b32 s9, 0x400, s9
	s_cmp_eq_u32 s5, 6
	s_cselect_b32 s9, 0xd00, s9
	s_lshl_b32 s12, s5, 3
	s_lshr_b64 s[12:13], s[22:23], s12
	s_and_b32 s12, s12, 0xff
	s_add_i32 s13, s12, 1
	v_readlane_b32 s16, v241, s12
	v_readlane_b32 s17, v241, s13
	v_mul_u32_u24_e32 v70, s9, v65
	s_mul_i32 s14, s8, s9
	s_add_i32 s14, s14, s7
	s_lshl_b32 s14, s14, 8
	v_add_lshl_u32 v70, v70, v64, 2
	s_add_u32 s18, s16, s14
	s_addc_u32 s19, s17, 0
	s_lshl_b32 s15, s9, 5
	global_load_dword v80, v70, s[18:19]
	s_add_u32 s18, s18, s15
	s_addc_u32 s19, s19, 0
	global_load_dword v81, v70, s[18:19]
	s_add_u32 s18, s18, s15
	s_addc_u32 s19, s19, 0
	global_load_dword v82, v70, s[18:19]
	s_add_u32 s18, s18, s15
	s_addc_u32 s19, s19, 0
	global_load_dword v83, v70, s[18:19]
	s_add_u32 s18, s18, s15
	s_addc_u32 s19, s19, 0
	global_load_dword v84, v70, s[18:19]
	s_add_u32 s18, s18, s15
	s_addc_u32 s19, s19, 0
	global_load_dword v85, v70, s[18:19]
	s_add_u32 s18, s18, s15
	s_addc_u32 s19, s19, 0
	global_load_dword v86, v70, s[18:19]
	s_add_u32 s18, s18, s15
	s_addc_u32 s19, s19, 0
	global_load_dword v87, v70, s[18:19]
	s_add_i32 s4, s2, 0x200
	s_mov_b32 s5, 0
	s_cmp_ge_u32 s4, 0x2c0
	s_addc_u32 s5, s5, 0
	s_cmp_ge_u32 s4, 0x580
	s_addc_u32 s5, s5, 0
	s_cmp_ge_u32 s4, 0x840
	s_addc_u32 s5, s5, 0
	s_cmp_ge_u32 s4, 0xb00
	s_addc_u32 s5, s5, 0
	s_cmp_ge_u32 s4, 0xdc0
	s_addc_u32 s5, s5, 0
	s_cmp_ge_u32 s4, 0x1080
	s_addc_u32 s5, s5, 0
	s_cmp_ge_u32 s4, 0x13c0
	s_addc_u32 s5, s5, 0
	s_mul_i32 s12, s5, 0x2c0
	s_cmp_eq_u32 s5, 7
	s_cselect_b32 s13, 0x80, 0
	s_add_i32 s12, s12, s13
	s_sub_i32 s6, s4, s12
	s_cmp_eq_u32 s5, 2
	s_cselect_b32 s14, 1, 0
	s_cmp_eq_u32 s5, 5
	s_cselect_b32 s14, 1, s14
	s_mul_i32 s12, s6, 0x5d2
	s_lshr_b32 s12, s12, 16
	s_mul_i32 s15, s12, 44
	s_sub_i32 s15, s6, s15
	s_lshr_b32 s13, s6, 4
	s_and_b32 s8, s6, 15
	s_cmp_eq_u32 s14, 1
	s_cselect_b32 s7, s12, s13
	s_cselect_b32 s8, s15, s8
	s_movk_i32 s10, 0x400
	s_cselect_b32 s10, 0xb00, s10
	s_movk_i32 s9, 0xb00
	s_cselect_b32 s9, 0x400, s9
	s_cmp_eq_u32 s5, 7
	s_cselect_b32 s9, 0x400, s9
	s_cmp_eq_u32 s5, 6
	s_cselect_b32 s9, 0xd00, s9
	s_lshl_b32 s12, s5, 3
	s_lshr_b64 s[12:13], s[22:23], s12
	s_and_b32 s12, s12, 0xff
	s_add_i32 s13, s12, 1
	v_readlane_b32 s16, v241, s12
	v_readlane_b32 s17, v241, s13
	v_mul_u32_u24_e32 v70, s9, v65
	s_mul_i32 s14, s8, s9
	s_add_i32 s14, s14, s7
	s_lshl_b32 s14, s14, 8
	v_add_lshl_u32 v70, v70, v64, 2
	s_add_u32 s18, s16, s14
	s_addc_u32 s19, s17, 0
	s_lshl_b32 s15, s9, 5
	global_load_dword v88, v70, s[18:19]
	s_add_u32 s18, s18, s15
	s_addc_u32 s19, s19, 0
	global_load_dword v89, v70, s[18:19]
	s_add_u32 s18, s18, s15
	s_addc_u32 s19, s19, 0
	global_load_dword v90, v70, s[18:19]
	s_add_u32 s18, s18, s15
	s_addc_u32 s19, s19, 0
	global_load_dword v91, v70, s[18:19]
	s_add_u32 s18, s18, s15
	s_addc_u32 s19, s19, 0
	global_load_dword v92, v70, s[18:19]
	s_add_u32 s18, s18, s15
	s_addc_u32 s19, s19, 0
	global_load_dword v93, v70, s[18:19]
	s_add_u32 s18, s18, s15
	s_addc_u32 s19, s19, 0
	global_load_dword v94, v70, s[18:19]
	s_add_u32 s18, s18, s15
	s_addc_u32 s19, s19, 0
	global_load_dword v95, v70, s[18:19]
	s_add_i32 s4, s2, 0x300
	s_mov_b32 s5, 0
	s_cmp_ge_u32 s4, 0x2c0
	s_addc_u32 s5, s5, 0
	s_cmp_ge_u32 s4, 0x580
	s_addc_u32 s5, s5, 0
	s_cmp_ge_u32 s4, 0x840
	s_addc_u32 s5, s5, 0
	s_cmp_ge_u32 s4, 0xb00
	s_addc_u32 s5, s5, 0
	s_cmp_ge_u32 s4, 0xdc0
	s_addc_u32 s5, s5, 0
	s_cmp_ge_u32 s4, 0x1080
	s_addc_u32 s5, s5, 0
	s_cmp_ge_u32 s4, 0x13c0
	s_addc_u32 s5, s5, 0
	s_mul_i32 s12, s5, 0x2c0
	s_cmp_eq_u32 s5, 7
	s_cselect_b32 s13, 0x80, 0
	s_add_i32 s12, s12, s13
	s_sub_i32 s6, s4, s12
	s_cmp_eq_u32 s5, 2
	s_cselect_b32 s14, 1, 0
	s_cmp_eq_u32 s5, 5
	s_cselect_b32 s14, 1, s14
	s_mul_i32 s12, s6, 0x5d2
	s_lshr_b32 s12, s12, 16
	s_mul_i32 s15, s12, 44
	s_sub_i32 s15, s6, s15
	s_lshr_b32 s13, s6, 4
	s_and_b32 s8, s6, 15
	s_cmp_eq_u32 s14, 1
	s_cselect_b32 s7, s12, s13
	s_cselect_b32 s8, s15, s8
	s_movk_i32 s10, 0x400
	s_cselect_b32 s10, 0xb00, s10
	s_movk_i32 s9, 0xb00
	s_cselect_b32 s9, 0x400, s9
	s_cmp_eq_u32 s5, 7
	s_cselect_b32 s9, 0x400, s9
	s_cmp_eq_u32 s5, 6
	s_cselect_b32 s9, 0xd00, s9
	s_lshl_b32 s12, s5, 3
	s_lshr_b64 s[12:13], s[22:23], s12
	s_and_b32 s12, s12, 0xff
	s_add_i32 s13, s12, 1
	v_readlane_b32 s16, v241, s12
	v_readlane_b32 s17, v241, s13
	v_mul_u32_u24_e32 v70, s9, v65
	s_mul_i32 s14, s8, s9
	s_add_i32 s14, s14, s7
	s_lshl_b32 s14, s14, 8
	v_add_lshl_u32 v70, v70, v64, 2
	s_add_u32 s18, s16, s14
	s_addc_u32 s19, s17, 0
	s_lshl_b32 s15, s9, 5
	global_load_dword v96, v70, s[18:19]
	s_add_u32 s18, s18, s15
	s_addc_u32 s19, s19, 0
	global_load_dword v97, v70, s[18:19]
	s_add_u32 s18, s18, s15
	s_addc_u32 s19, s19, 0
	global_load_dword v98, v70, s[18:19]
	s_add_u32 s18, s18, s15
	s_addc_u32 s19, s19, 0
	global_load_dword v99, v70, s[18:19]
	s_add_u32 s18, s18, s15
	s_addc_u32 s19, s19, 0
	global_load_dword v100, v70, s[18:19]
	s_add_u32 s18, s18, s15
	s_addc_u32 s19, s19, 0
	global_load_dword v101, v70, s[18:19]
	s_add_u32 s18, s18, s15
	s_addc_u32 s19, s19, 0
	global_load_dword v102, v70, s[18:19]
	s_add_u32 s18, s18, s15
	s_addc_u32 s19, s19, 0
	global_load_dword v103, v70, s[18:19]
	s_waitcnt vmcnt(24)
	ds_write_b32 v68, v72
	ds_write_b32 v68, v73 offset:2080
	ds_write_b32 v68, v74 offset:4160
	ds_write_b32 v68, v75 offset:6240
	ds_write_b32 v68, v76 offset:8320
	ds_write_b32 v68, v77 offset:10400
	ds_write_b32 v68, v78 offset:12480
	ds_write_b32 v68, v79 offset:14560
	s_waitcnt lgkmcnt(0)
	s_barrier
	s_mov_b32 s4, s2
	s_mov_b32 s5, 0
	s_cmp_ge_u32 s4, 0x2c0
	s_addc_u32 s5, s5, 0
	s_cmp_ge_u32 s4, 0x580
	s_addc_u32 s5, s5, 0
	s_cmp_ge_u32 s4, 0x840
	s_addc_u32 s5, s5, 0
	s_cmp_ge_u32 s4, 0xb00
	s_addc_u32 s5, s5, 0
	s_cmp_ge_u32 s4, 0xdc0
	s_addc_u32 s5, s5, 0
	s_cmp_ge_u32 s4, 0x1080
	s_addc_u32 s5, s5, 0
	s_cmp_ge_u32 s4, 0x13c0
	s_addc_u32 s5, s5, 0
	s_mul_i32 s12, s5, 0x2c0
	s_cmp_eq_u32 s5, 7
	s_cselect_b32 s13, 0x80, 0
	s_add_i32 s12, s12, s13
	s_sub_i32 s6, s4, s12
	s_cmp_eq_u32 s5, 2
	s_cselect_b32 s14, 1, 0
	s_cmp_eq_u32 s5, 5
	s_cselect_b32 s14, 1, s14
	s_mul_i32 s12, s6, 0x5d2
	s_lshr_b32 s12, s12, 16
	s_mul_i32 s15, s12, 44
	s_sub_i32 s15, s6, s15
	s_lshr_b32 s13, s6, 4
	s_and_b32 s8, s6, 15
	s_cmp_eq_u32 s14, 1
	s_cselect_b32 s7, s12, s13
	s_cselect_b32 s8, s15, s8
	s_movk_i32 s10, 0x400
	s_cselect_b32 s10, 0xb00, s10
	s_movk_i32 s9, 0xb00
	s_cselect_b32 s9, 0x400, s9
	s_cmp_eq_u32 s5, 7
	s_cselect_b32 s9, 0x400, s9
	s_cmp_eq_u32 s5, 6
	s_cselect_b32 s9, 0xd00, s9
	s_lshl_b32 s12, s7, 6
	s_lshr_b32 s13, s7, 1
	s_lshl_b32 s13, s13, 8
	s_and_b32 s15, s7, 1
	s_lshl_b32 s15, s15, 6
	s_add_i32 s13, s13, s15
	s_and_b32 s15, s5, 1
	s_cmp_eq_u32 s5, 1
	s_cselect_b32 s15, 0x80, 0
	s_cmp_eq_u32 s5, 4
	s_cselect_b32 s15, 0x80, s15
	s_add_i32 s13, s13, s15
	s_cmp_eq_u32 s9, 0xb00
	s_cselect_b32 s12, s13, s12
	s_mov_b32 s14, 0x30000
	s_cmp_eq_u32 s5, 1
	s_cselect_b32 s14, 0x30000, s14
	s_cmp_eq_u32 s5, 2
	s_cselect_b32 s14, 0xb30000, s14
	s_cmp_eq_u32 s5, 3
	s_cselect_b32 s14, 0x10b0000, s14
	s_cmp_eq_u32 s5, 4
	s_cselect_b32 s14, 0x10b0000, s14
	s_cmp_eq_u32 s5, 5
	s_cselect_b32 s14, 0x1bb0000, s14
	s_cmp_eq_u32 s5, 6
	s_cselect_b32 s14, 0x2130000, s14
	s_cmp_eq_u32 s5, 7
	s_cselect_b32 s14, 0x28f0000, s14
	s_cmp_eq_u32 s5, 6
	s_cselect_b32 s15, 1, 0
	s_cmp_ge_u32 s7, 24
	s_cselect_b32 s13, s15, 0
	s_cmp_eq_u32 s13, 1
	s_cselect_b32 s14, 0x2430000, s14
	s_cselect_b32 s13, 0x600, 0
	s_sub_i32 s12, s12, s13
	s_mul_i32 s12, s12, s10
	s_lshl_b32 s13, s8, 6
	s_add_i32 s12, s12, s13
	s_lshl_b32 s12, s12, 1
	s_add_u32 s12, s12, s14
	s_add_u32 s20, s30, s12
	s_addc_u32 s21, s31, 0
	v_mul_u32_u24_e32 v71, s10, v66
	v_add_lshl_u32 v71, v71, v67, 1
	ds_read_b32 v104, v69
	ds_read_b32 v105, v69 offset:260
	ds_read_b32 v106, v69 offset:520
	ds_read_b32 v107, v69 offset:780
	ds_read_b32 v108, v69 offset:1040
	ds_read_b32 v109, v69 offset:1300
	ds_read_b32 v110, v69 offset:1560
	ds_read_b32 v111, v69 offset:1820
	s_waitcnt lgkmcnt(0)
	v_cvt_pk_bf16_f32 v112, v104, v105
	v_cvt_pk_bf16_f32 v113, v106, v107
	v_cvt_pk_bf16_f32 v114, v108, v109
	v_cvt_pk_bf16_f32 v115, v110, v111
	global_store_dwordx4 v71, v[112:115], s[20:21]
	s_barrier
	s_add_i32 s4, s2, 0x400
	s_mov_b32 s5, 0
	s_cmp_ge_u32 s4, 0x2c0
	s_addc_u32 s5, s5, 0
	s_cmp_ge_u32 s4, 0x580
	s_addc_u32 s5, s5, 0
	s_cmp_ge_u32 s4, 0x840
	s_addc_u32 s5, s5, 0
	s_cmp_ge_u32 s4, 0xb00
	s_addc_u32 s5, s5, 0
	s_cmp_ge_u32 s4, 0xdc0
	s_addc_u32 s5, s5, 0
	s_cmp_ge_u32 s4, 0x1080
	s_addc_u32 s5, s5, 0
	s_cmp_ge_u32 s4, 0x13c0
	s_addc_u32 s5, s5, 0
	s_mul_i32 s12, s5, 0x2c0
	s_cmp_eq_u32 s5, 7
	s_cselect_b32 s13, 0x80, 0
	s_add_i32 s12, s12, s13
	s_sub_i32 s6, s4, s12
	s_cmp_eq_u32 s5, 2
	s_cselect_b32 s14, 1, 0
	s_cmp_eq_u32 s5, 5
	s_cselect_b32 s14, 1, s14
	s_mul_i32 s12, s6, 0x5d2
	s_lshr_b32 s12, s12, 16
	s_mul_i32 s15, s12, 44
	s_sub_i32 s15, s6, s15
	s_lshr_b32 s13, s6, 4
	s_and_b32 s8, s6, 15
	s_cmp_eq_u32 s14, 1
	s_cselect_b32 s7, s12, s13
	s_cselect_b32 s8, s15, s8
	s_movk_i32 s10, 0x400
	s_cselect_b32 s10, 0xb00, s10
	s_movk_i32 s9, 0xb00
	s_cselect_b32 s9, 0x400, s9
	s_cmp_eq_u32 s5, 7
	s_cselect_b32 s9, 0x400, s9
	s_cmp_eq_u32 s5, 6
	s_cselect_b32 s9, 0xd00, s9
	s_lshl_b32 s12, s5, 3
	s_lshr_b64 s[12:13], s[22:23], s12
	s_and_b32 s12, s12, 0xff
	s_add_i32 s13, s12, 1
	v_readlane_b32 s16, v241, s12
	v_readlane_b32 s17, v241, s13
	v_mul_u32_u24_e32 v70, s9, v65
	s_mul_i32 s14, s8, s9
	s_add_i32 s14, s14, s7
	s_lshl_b32 s14, s14, 8
	v_add_lshl_u32 v70, v70, v64, 2
	s_add_u32 s18, s16, s14
	s_addc_u32 s19, s17, 0
	s_lshl_b32 s15, s9, 5
	global_load_dword v72, v70, s[18:19]
	s_add_u32 s18, s18, s15
	s_addc_u32 s19, s19, 0
	global_load_dword v73, v70, s[18:19]
	s_add_u32 s18, s18, s15
	s_addc_u32 s19, s19, 0
	global_load_dword v74, v70, s[18:19]
	s_add_u32 s18, s18, s15
	s_addc_u32 s19, s19, 0
	global_load_dword v75, v70, s[18:19]
	s_add_u32 s18, s18, s15
	s_addc_u32 s19, s19, 0
	global_load_dword v76, v70, s[18:19]
	s_add_u32 s18, s18, s15
	s_addc_u32 s19, s19, 0
	global_load_dword v77, v70, s[18:19]
	s_add_u32 s18, s18, s15
	s_addc_u32 s19, s19, 0
	global_load_dword v78, v70, s[18:19]
	s_add_u32 s18, s18, s15
	s_addc_u32 s19, s19, 0
	global_load_dword v79, v70, s[18:19]
	s_waitcnt vmcnt(25)
	ds_write_b32 v68, v80
	ds_write_b32 v68, v81 offset:2080
	ds_write_b32 v68, v82 offset:4160
	ds_write_b32 v68, v83 offset:6240
	ds_write_b32 v68, v84 offset:8320
	ds_write_b32 v68, v85 offset:10400
	ds_write_b32 v68, v86 offset:12480
	ds_write_b32 v68, v87 offset:14560
	s_waitcnt lgkmcnt(0)
	s_barrier
	s_add_i32 s4, s2, 0x100
	s_mov_b32 s5, 0
	s_cmp_ge_u32 s4, 0x2c0
	s_addc_u32 s5, s5, 0
	s_cmp_ge_u32 s4, 0x580
	s_addc_u32 s5, s5, 0
	s_cmp_ge_u32 s4, 0x840
	s_addc_u32 s5, s5, 0
	s_cmp_ge_u32 s4, 0xb00
	s_addc_u32 s5, s5, 0
	s_cmp_ge_u32 s4, 0xdc0
	s_addc_u32 s5, s5, 0
	s_cmp_ge_u32 s4, 0x1080
	s_addc_u32 s5, s5, 0
	s_cmp_ge_u32 s4, 0x13c0
	s_addc_u32 s5, s5, 0
	s_mul_i32 s12, s5, 0x2c0
	s_cmp_eq_u32 s5, 7
	s_cselect_b32 s13, 0x80, 0
	s_add_i32 s12, s12, s13
	s_sub_i32 s6, s4, s12
	s_cmp_eq_u32 s5, 2
	s_cselect_b32 s14, 1, 0
	s_cmp_eq_u32 s5, 5
	s_cselect_b32 s14, 1, s14
	s_mul_i32 s12, s6, 0x5d2
	s_lshr_b32 s12, s12, 16
	s_mul_i32 s15, s12, 44
	s_sub_i32 s15, s6, s15
	s_lshr_b32 s13, s6, 4
	s_and_b32 s8, s6, 15
	s_cmp_eq_u32 s14, 1
	s_cselect_b32 s7, s12, s13
	s_cselect_b32 s8, s15, s8
	s_movk_i32 s10, 0x400
	s_cselect_b32 s10, 0xb00, s10
	s_movk_i32 s9, 0xb00
	s_cselect_b32 s9, 0x400, s9
	s_cmp_eq_u32 s5, 7
	s_cselect_b32 s9, 0x400, s9
	s_cmp_eq_u32 s5, 6
	s_cselect_b32 s9, 0xd00, s9
	s_lshl_b32 s12, s7, 6
	s_lshr_b32 s13, s7, 1
	s_lshl_b32 s13, s13, 8
	s_and_b32 s15, s7, 1
	s_lshl_b32 s15, s15, 6
	s_add_i32 s13, s13, s15
	s_and_b32 s15, s5, 1
	s_cmp_eq_u32 s5, 1
	s_cselect_b32 s15, 0x80, 0
	s_cmp_eq_u32 s5, 4
	s_cselect_b32 s15, 0x80, s15
	s_add_i32 s13, s13, s15
	s_cmp_eq_u32 s9, 0xb00
	s_cselect_b32 s12, s13, s12
	s_mov_b32 s14, 0x30000
	s_cmp_eq_u32 s5, 1
	s_cselect_b32 s14, 0x30000, s14
	s_cmp_eq_u32 s5, 2
	s_cselect_b32 s14, 0xb30000, s14
	s_cmp_eq_u32 s5, 3
	s_cselect_b32 s14, 0x10b0000, s14
	s_cmp_eq_u32 s5, 4
	s_cselect_b32 s14, 0x10b0000, s14
	s_cmp_eq_u32 s5, 5
	s_cselect_b32 s14, 0x1bb0000, s14
	s_cmp_eq_u32 s5, 6
	s_cselect_b32 s14, 0x2130000, s14
	s_cmp_eq_u32 s5, 7
	s_cselect_b32 s14, 0x28f0000, s14
	s_cmp_eq_u32 s5, 6
	s_cselect_b32 s15, 1, 0
	s_cmp_ge_u32 s7, 24
	s_cselect_b32 s13, s15, 0
	s_cmp_eq_u32 s13, 1
	s_cselect_b32 s14, 0x2430000, s14
	s_cselect_b32 s13, 0x600, 0
	s_sub_i32 s12, s12, s13
	s_mul_i32 s12, s12, s10
	s_lshl_b32 s13, s8, 6
	s_add_i32 s12, s12, s13
	s_lshl_b32 s12, s12, 1
	s_add_u32 s12, s12, s14
	s_add_u32 s20, s30, s12
	s_addc_u32 s21, s31, 0
	v_mul_u32_u24_e32 v71, s10, v66
	v_add_lshl_u32 v71, v71, v67, 1
	ds_read_b32 v104, v69
	ds_read_b32 v105, v69 offset:260
	ds_read_b32 v106, v69 offset:520
	ds_read_b32 v107, v69 offset:780
	ds_read_b32 v108, v69 offset:1040
	ds_read_b32 v109, v69 offset:1300
	ds_read_b32 v110, v69 offset:1560
	ds_read_b32 v111, v69 offset:1820
	s_waitcnt lgkmcnt(0)
	v_cvt_pk_bf16_f32 v116, v104, v105
	v_cvt_pk_bf16_f32 v117, v106, v107
	v_cvt_pk_bf16_f32 v118, v108, v109
	v_cvt_pk_bf16_f32 v119, v110, v111
	global_store_dwordx4 v71, v[116:119], s[20:21]
	s_barrier
	s_add_i32 s4, s2, 0x500
	s_mov_b32 s5, 0
	s_cmp_ge_u32 s4, 0x2c0
	s_addc_u32 s5, s5, 0
	s_cmp_ge_u32 s4, 0x580
	s_addc_u32 s5, s5, 0
	s_cmp_ge_u32 s4, 0x840
	s_addc_u32 s5, s5, 0
	s_cmp_ge_u32 s4, 0xb00
	s_addc_u32 s5, s5, 0
	s_cmp_ge_u32 s4, 0xdc0
	s_addc_u32 s5, s5, 0
	s_cmp_ge_u32 s4, 0x1080
	s_addc_u32 s5, s5, 0
	s_cmp_ge_u32 s4, 0x13c0
	s_addc_u32 s5, s5, 0
	s_mul_i32 s12, s5, 0x2c0
	s_cmp_eq_u32 s5, 7
	s_cselect_b32 s13, 0x80, 0
	s_add_i32 s12, s12, s13
	s_sub_i32 s6, s4, s12
	s_cmp_eq_u32 s5, 2
	s_cselect_b32 s14, 1, 0
	s_cmp_eq_u32 s5, 5
	s_cselect_b32 s14, 1, s14
	s_mul_i32 s12, s6, 0x5d2
	s_lshr_b32 s12, s12, 16
	s_mul_i32 s15, s12, 44
	s_sub_i32 s15, s6, s15
	s_lshr_b32 s13, s6, 4
	s_and_b32 s8, s6, 15
	s_cmp_eq_u32 s14, 1
	s_cselect_b32 s7, s12, s13
	s_cselect_b32 s8, s15, s8
	s_movk_i32 s10, 0x400
	s_cselect_b32 s10, 0xb00, s10
	s_movk_i32 s9, 0xb00
	s_cselect_b32 s9, 0x400, s9
	s_cmp_eq_u32 s5, 7
	s_cselect_b32 s9, 0x400, s9
	s_cmp_eq_u32 s5, 6
	s_cselect_b32 s9, 0xd00, s9
	s_lshl_b32 s12, s5, 3
	s_lshr_b64 s[12:13], s[22:23], s12
	s_and_b32 s12, s12, 0xff
	s_add_i32 s13, s12, 1
	v_readlane_b32 s16, v241, s12
	v_readlane_b32 s17, v241, s13
	v_mul_u32_u24_e32 v70, s9, v65
	s_mul_i32 s14, s8, s9
	s_add_i32 s14, s14, s7
	s_lshl_b32 s14, s14, 8
	v_add_lshl_u32 v70, v70, v64, 2
	s_add_u32 s18, s16, s14
	s_addc_u32 s19, s17, 0
	s_lshl_b32 s15, s9, 5
	global_load_dword v80, v70, s[18:19]
	s_add_u32 s18, s18, s15
	s_addc_u32 s19, s19, 0
	global_load_dword v81, v70, s[18:19]
	s_add_u32 s18, s18, s15
	s_addc_u32 s19, s19, 0
	global_load_dword v82, v70, s[18:19]
	s_add_u32 s18, s18, s15
	s_addc_u32 s19, s19, 0
	global_load_dword v83, v70, s[18:19]
	s_add_u32 s18, s18, s15
	s_addc_u32 s19, s19, 0
	global_load_dword v84, v70, s[18:19]
	s_add_u32 s18, s18, s15
	s_addc_u32 s19, s19, 0
	global_load_dword v85, v70, s[18:19]
	s_add_u32 s18, s18, s15
	s_addc_u32 s19, s19, 0
	global_load_dword v86, v70, s[18:19]
	s_add_u32 s18, s18, s15
	s_addc_u32 s19, s19, 0
	global_load_dword v87, v70, s[18:19]
	s_waitcnt vmcnt(26)
	ds_write_b32 v68, v88
	ds_write_b32 v68, v89 offset:2080
	ds_write_b32 v68, v90 offset:4160
	ds_write_b32 v68, v91 offset:6240
	ds_write_b32 v68, v92 offset:8320
	ds_write_b32 v68, v93 offset:10400
	ds_write_b32 v68, v94 offset:12480
	ds_write_b32 v68, v95 offset:14560
	s_waitcnt lgkmcnt(0)
	s_barrier
	s_add_i32 s4, s2, 0x200
	s_mov_b32 s5, 0
	s_cmp_ge_u32 s4, 0x2c0
	s_addc_u32 s5, s5, 0
	s_cmp_ge_u32 s4, 0x580
	s_addc_u32 s5, s5, 0
	s_cmp_ge_u32 s4, 0x840
	s_addc_u32 s5, s5, 0
	s_cmp_ge_u32 s4, 0xb00
	s_addc_u32 s5, s5, 0
	s_cmp_ge_u32 s4, 0xdc0
	s_addc_u32 s5, s5, 0
	s_cmp_ge_u32 s4, 0x1080
	s_addc_u32 s5, s5, 0
	s_cmp_ge_u32 s4, 0x13c0
	s_addc_u32 s5, s5, 0
	s_mul_i32 s12, s5, 0x2c0
	s_cmp_eq_u32 s5, 7
	s_cselect_b32 s13, 0x80, 0
	s_add_i32 s12, s12, s13
	s_sub_i32 s6, s4, s12
	s_cmp_eq_u32 s5, 2
	s_cselect_b32 s14, 1, 0
	s_cmp_eq_u32 s5, 5
	s_cselect_b32 s14, 1, s14
	s_mul_i32 s12, s6, 0x5d2
	s_lshr_b32 s12, s12, 16
	s_mul_i32 s15, s12, 44
	s_sub_i32 s15, s6, s15
	s_lshr_b32 s13, s6, 4
	s_and_b32 s8, s6, 15
	s_cmp_eq_u32 s14, 1
	s_cselect_b32 s7, s12, s13
	s_cselect_b32 s8, s15, s8
	s_movk_i32 s10, 0x400
	s_cselect_b32 s10, 0xb00, s10
	s_movk_i32 s9, 0xb00
	s_cselect_b32 s9, 0x400, s9
	s_cmp_eq_u32 s5, 7
	s_cselect_b32 s9, 0x400, s9
	s_cmp_eq_u32 s5, 6
	s_cselect_b32 s9, 0xd00, s9
	s_lshl_b32 s12, s7, 6
	s_lshr_b32 s13, s7, 1
	s_lshl_b32 s13, s13, 8
	s_and_b32 s15, s7, 1
	s_lshl_b32 s15, s15, 6
	s_add_i32 s13, s13, s15
	s_and_b32 s15, s5, 1
	s_cmp_eq_u32 s5, 1
	s_cselect_b32 s15, 0x80, 0
	s_cmp_eq_u32 s5, 4
	s_cselect_b32 s15, 0x80, s15
	s_add_i32 s13, s13, s15
	s_cmp_eq_u32 s9, 0xb00
	s_cselect_b32 s12, s13, s12
	s_mov_b32 s14, 0x30000
	s_cmp_eq_u32 s5, 1
	s_cselect_b32 s14, 0x30000, s14
	s_cmp_eq_u32 s5, 2
	s_cselect_b32 s14, 0xb30000, s14
	s_cmp_eq_u32 s5, 3
	s_cselect_b32 s14, 0x10b0000, s14
	s_cmp_eq_u32 s5, 4
	s_cselect_b32 s14, 0x10b0000, s14
	s_cmp_eq_u32 s5, 5
	s_cselect_b32 s14, 0x1bb0000, s14
	s_cmp_eq_u32 s5, 6
	s_cselect_b32 s14, 0x2130000, s14
	s_cmp_eq_u32 s5, 7
	s_cselect_b32 s14, 0x28f0000, s14
	s_cmp_eq_u32 s5, 6
	s_cselect_b32 s15, 1, 0
	s_cmp_ge_u32 s7, 24
	s_cselect_b32 s13, s15, 0
	s_cmp_eq_u32 s13, 1
	s_cselect_b32 s14, 0x2430000, s14
	s_cselect_b32 s13, 0x600, 0
	s_sub_i32 s12, s12, s13
	s_mul_i32 s12, s12, s10
	s_lshl_b32 s13, s8, 6
	s_add_i32 s12, s12, s13
	s_lshl_b32 s12, s12, 1
	s_add_u32 s12, s12, s14
	s_add_u32 s20, s30, s12
	s_addc_u32 s21, s31, 0
	v_mul_u32_u24_e32 v71, s10, v66
	v_add_lshl_u32 v71, v71, v67, 1
	ds_read_b32 v104, v69
	ds_read_b32 v105, v69 offset:260
	ds_read_b32 v106, v69 offset:520
	ds_read_b32 v107, v69 offset:780
	ds_read_b32 v108, v69 offset:1040
	ds_read_b32 v109, v69 offset:1300
	ds_read_b32 v110, v69 offset:1560
	ds_read_b32 v111, v69 offset:1820
	s_waitcnt lgkmcnt(0)
	v_cvt_pk_bf16_f32 v112, v104, v105
	v_cvt_pk_bf16_f32 v113, v106, v107
	v_cvt_pk_bf16_f32 v114, v108, v109
	v_cvt_pk_bf16_f32 v115, v110, v111
	global_store_dwordx4 v71, v[112:115], s[20:21]
	s_barrier
	s_add_i32 s4, s2, 0x600
	s_mov_b32 s5, 0
	s_cmp_ge_u32 s4, 0x2c0
	s_addc_u32 s5, s5, 0
	s_cmp_ge_u32 s4, 0x580
	s_addc_u32 s5, s5, 0
	s_cmp_ge_u32 s4, 0x840
	s_addc_u32 s5, s5, 0
	s_cmp_ge_u32 s4, 0xb00
	s_addc_u32 s5, s5, 0
	s_cmp_ge_u32 s4, 0xdc0
	s_addc_u32 s5, s5, 0
	s_cmp_ge_u32 s4, 0x1080
	s_addc_u32 s5, s5, 0
	s_cmp_ge_u32 s4, 0x13c0
	s_addc_u32 s5, s5, 0
	s_mul_i32 s12, s5, 0x2c0
	s_cmp_eq_u32 s5, 7
	s_cselect_b32 s13, 0x80, 0
	s_add_i32 s12, s12, s13
	s_sub_i32 s6, s4, s12
	s_cmp_eq_u32 s5, 2
	s_cselect_b32 s14, 1, 0
	s_cmp_eq_u32 s5, 5
	s_cselect_b32 s14, 1, s14
	s_mul_i32 s12, s6, 0x5d2
	s_lshr_b32 s12, s12, 16
	s_mul_i32 s15, s12, 44
	s_sub_i32 s15, s6, s15
	s_lshr_b32 s13, s6, 4
	s_and_b32 s8, s6, 15
	s_cmp_eq_u32 s14, 1
	s_cselect_b32 s7, s12, s13
	s_cselect_b32 s8, s15, s8
	s_movk_i32 s10, 0x400
	s_cselect_b32 s10, 0xb00, s10
	s_movk_i32 s9, 0xb00
	s_cselect_b32 s9, 0x400, s9
	s_cmp_eq_u32 s5, 7
	s_cselect_b32 s9, 0x400, s9
	s_cmp_eq_u32 s5, 6
	s_cselect_b32 s9, 0xd00, s9
	s_lshl_b32 s12, s5, 3
	s_lshr_b64 s[12:13], s[22:23], s12
	s_and_b32 s12, s12, 0xff
	s_add_i32 s13, s12, 1
	v_readlane_b32 s16, v241, s12
	v_readlane_b32 s17, v241, s13
	v_mul_u32_u24_e32 v70, s9, v65
	s_mul_i32 s14, s8, s9
	s_add_i32 s14, s14, s7
	s_lshl_b32 s14, s14, 8
	v_add_lshl_u32 v70, v70, v64, 2
	s_add_u32 s18, s16, s14
	s_addc_u32 s19, s17, 0
	s_lshl_b32 s15, s9, 5
	global_load_dword v88, v70, s[18:19]
	s_add_u32 s18, s18, s15
	s_addc_u32 s19, s19, 0
	global_load_dword v89, v70, s[18:19]
	s_add_u32 s18, s18, s15
	s_addc_u32 s19, s19, 0
	global_load_dword v90, v70, s[18:19]
	s_add_u32 s18, s18, s15
	s_addc_u32 s19, s19, 0
	global_load_dword v91, v70, s[18:19]
	s_add_u32 s18, s18, s15
	s_addc_u32 s19, s19, 0
	global_load_dword v92, v70, s[18:19]
	s_add_u32 s18, s18, s15
	s_addc_u32 s19, s19, 0
	global_load_dword v93, v70, s[18:19]
	s_add_u32 s18, s18, s15
	s_addc_u32 s19, s19, 0
	global_load_dword v94, v70, s[18:19]
	s_add_u32 s18, s18, s15
	s_addc_u32 s19, s19, 0
	global_load_dword v95, v70, s[18:19]
	s_waitcnt vmcnt(27)
	ds_write_b32 v68, v96
	ds_write_b32 v68, v97 offset:2080
	ds_write_b32 v68, v98 offset:4160
	ds_write_b32 v68, v99 offset:6240
	ds_write_b32 v68, v100 offset:8320
	ds_write_b32 v68, v101 offset:10400
	ds_write_b32 v68, v102 offset:12480
	ds_write_b32 v68, v103 offset:14560
	s_waitcnt lgkmcnt(0)
	s_barrier
	s_add_i32 s4, s2, 0x300
	s_mov_b32 s5, 0
	s_cmp_ge_u32 s4, 0x2c0
	s_addc_u32 s5, s5, 0
	s_cmp_ge_u32 s4, 0x580
	s_addc_u32 s5, s5, 0
	s_cmp_ge_u32 s4, 0x840
	s_addc_u32 s5, s5, 0
	s_cmp_ge_u32 s4, 0xb00
	s_addc_u32 s5, s5, 0
	s_cmp_ge_u32 s4, 0xdc0
	s_addc_u32 s5, s5, 0
	s_cmp_ge_u32 s4, 0x1080
	s_addc_u32 s5, s5, 0
	s_cmp_ge_u32 s4, 0x13c0
	s_addc_u32 s5, s5, 0
	s_mul_i32 s12, s5, 0x2c0
	s_cmp_eq_u32 s5, 7
	s_cselect_b32 s13, 0x80, 0
	s_add_i32 s12, s12, s13
	s_sub_i32 s6, s4, s12
	s_cmp_eq_u32 s5, 2
	s_cselect_b32 s14, 1, 0
	s_cmp_eq_u32 s5, 5
	s_cselect_b32 s14, 1, s14
	s_mul_i32 s12, s6, 0x5d2
	s_lshr_b32 s12, s12, 16
	s_mul_i32 s15, s12, 44
	s_sub_i32 s15, s6, s15
	s_lshr_b32 s13, s6, 4
	s_and_b32 s8, s6, 15
	s_cmp_eq_u32 s14, 1
	s_cselect_b32 s7, s12, s13
	s_cselect_b32 s8, s15, s8
	s_movk_i32 s10, 0x400
	s_cselect_b32 s10, 0xb00, s10
	s_movk_i32 s9, 0xb00
	s_cselect_b32 s9, 0x400, s9
	s_cmp_eq_u32 s5, 7
	s_cselect_b32 s9, 0x400, s9
	s_cmp_eq_u32 s5, 6
	s_cselect_b32 s9, 0xd00, s9
	s_lshl_b32 s12, s7, 6
	s_lshr_b32 s13, s7, 1
	s_lshl_b32 s13, s13, 8
	s_and_b32 s15, s7, 1
	s_lshl_b32 s15, s15, 6
	s_add_i32 s13, s13, s15
	s_and_b32 s15, s5, 1
	s_cmp_eq_u32 s5, 1
	s_cselect_b32 s15, 0x80, 0
	s_cmp_eq_u32 s5, 4
	s_cselect_b32 s15, 0x80, s15
	s_add_i32 s13, s13, s15
	s_cmp_eq_u32 s9, 0xb00
	s_cselect_b32 s12, s13, s12
	s_mov_b32 s14, 0x30000
	s_cmp_eq_u32 s5, 1
	s_cselect_b32 s14, 0x30000, s14
	s_cmp_eq_u32 s5, 2
	s_cselect_b32 s14, 0xb30000, s14
	s_cmp_eq_u32 s5, 3
	s_cselect_b32 s14, 0x10b0000, s14
	s_cmp_eq_u32 s5, 4
	s_cselect_b32 s14, 0x10b0000, s14
	s_cmp_eq_u32 s5, 5
	s_cselect_b32 s14, 0x1bb0000, s14
	s_cmp_eq_u32 s5, 6
	s_cselect_b32 s14, 0x2130000, s14
	s_cmp_eq_u32 s5, 7
	s_cselect_b32 s14, 0x28f0000, s14
	s_cmp_eq_u32 s5, 6
	s_cselect_b32 s15, 1, 0
	s_cmp_ge_u32 s7, 24
	s_cselect_b32 s13, s15, 0
	s_cmp_eq_u32 s13, 1
	s_cselect_b32 s14, 0x2430000, s14
	s_cselect_b32 s13, 0x600, 0
	s_sub_i32 s12, s12, s13
	s_mul_i32 s12, s12, s10
	s_lshl_b32 s13, s8, 6
	s_add_i32 s12, s12, s13
	s_lshl_b32 s12, s12, 1
	s_add_u32 s12, s12, s14
	s_add_u32 s20, s30, s12
	s_addc_u32 s21, s31, 0
	v_mul_u32_u24_e32 v71, s10, v66
	v_add_lshl_u32 v71, v71, v67, 1
	ds_read_b32 v104, v69
	ds_read_b32 v105, v69 offset:260
	ds_read_b32 v106, v69 offset:520
	ds_read_b32 v107, v69 offset:780
	ds_read_b32 v108, v69 offset:1040
	ds_read_b32 v109, v69 offset:1300
	ds_read_b32 v110, v69 offset:1560
	ds_read_b32 v111, v69 offset:1820
	s_waitcnt lgkmcnt(0)
	v_cvt_pk_bf16_f32 v116, v104, v105
	v_cvt_pk_bf16_f32 v117, v106, v107
	v_cvt_pk_bf16_f32 v118, v108, v109
	v_cvt_pk_bf16_f32 v119, v110, v111
	global_store_dwordx4 v71, v[116:119], s[20:21]
	s_barrier
	s_add_i32 s4, s2, 0x700
	s_mov_b32 s5, 0
	s_cmp_ge_u32 s4, 0x2c0
	s_addc_u32 s5, s5, 0
	s_cmp_ge_u32 s4, 0x580
	s_addc_u32 s5, s5, 0
	s_cmp_ge_u32 s4, 0x840
	s_addc_u32 s5, s5, 0
	s_cmp_ge_u32 s4, 0xb00
	s_addc_u32 s5, s5, 0
	s_cmp_ge_u32 s4, 0xdc0
	s_addc_u32 s5, s5, 0
	s_cmp_ge_u32 s4, 0x1080
	s_addc_u32 s5, s5, 0
	s_cmp_ge_u32 s4, 0x13c0
	s_addc_u32 s5, s5, 0
	s_mul_i32 s12, s5, 0x2c0
	s_cmp_eq_u32 s5, 7
	s_cselect_b32 s13, 0x80, 0
	s_add_i32 s12, s12, s13
	s_sub_i32 s6, s4, s12
	s_cmp_eq_u32 s5, 2
	s_cselect_b32 s14, 1, 0
	s_cmp_eq_u32 s5, 5
	s_cselect_b32 s14, 1, s14
	s_mul_i32 s12, s6, 0x5d2
	s_lshr_b32 s12, s12, 16
	s_mul_i32 s15, s12, 44
	s_sub_i32 s15, s6, s15
	s_lshr_b32 s13, s6, 4
	s_and_b32 s8, s6, 15
	s_cmp_eq_u32 s14, 1
	s_cselect_b32 s7, s12, s13
	s_cselect_b32 s8, s15, s8
	s_movk_i32 s10, 0x400
	s_cselect_b32 s10, 0xb00, s10
	s_movk_i32 s9, 0xb00
	s_cselect_b32 s9, 0x400, s9
	s_cmp_eq_u32 s5, 7
	s_cselect_b32 s9, 0x400, s9
	s_cmp_eq_u32 s5, 6
	s_cselect_b32 s9, 0xd00, s9
	s_lshl_b32 s12, s5, 3
	s_lshr_b64 s[12:13], s[22:23], s12
	s_and_b32 s12, s12, 0xff
	s_add_i32 s13, s12, 1
	v_readlane_b32 s16, v241, s12
	v_readlane_b32 s17, v241, s13
	v_mul_u32_u24_e32 v70, s9, v65
	s_mul_i32 s14, s8, s9
	s_add_i32 s14, s14, s7
	s_lshl_b32 s14, s14, 8
	v_add_lshl_u32 v70, v70, v64, 2
	s_add_u32 s18, s16, s14
	s_addc_u32 s19, s17, 0
	s_lshl_b32 s15, s9, 5
	global_load_dword v96, v70, s[18:19]
	s_add_u32 s18, s18, s15
	s_addc_u32 s19, s19, 0
	global_load_dword v97, v70, s[18:19]
	s_add_u32 s18, s18, s15
	s_addc_u32 s19, s19, 0
	global_load_dword v98, v70, s[18:19]
	s_add_u32 s18, s18, s15
	s_addc_u32 s19, s19, 0
	global_load_dword v99, v70, s[18:19]
	s_add_u32 s18, s18, s15
	s_addc_u32 s19, s19, 0
	global_load_dword v100, v70, s[18:19]
	s_add_u32 s18, s18, s15
	s_addc_u32 s19, s19, 0
	global_load_dword v101, v70, s[18:19]
	s_add_u32 s18, s18, s15
	s_addc_u32 s19, s19, 0
	global_load_dword v102, v70, s[18:19]
	s_add_u32 s18, s18, s15
	s_addc_u32 s19, s19, 0
	global_load_dword v103, v70, s[18:19]
	s_waitcnt vmcnt(27)
	ds_write_b32 v68, v72
	ds_write_b32 v68, v73 offset:2080
	ds_write_b32 v68, v74 offset:4160
	ds_write_b32 v68, v75 offset:6240
	ds_write_b32 v68, v76 offset:8320
	ds_write_b32 v68, v77 offset:10400
	ds_write_b32 v68, v78 offset:12480
	ds_write_b32 v68, v79 offset:14560
	s_waitcnt lgkmcnt(0)
	s_barrier
	s_add_i32 s4, s2, 0x400
	s_mov_b32 s5, 0
	s_cmp_ge_u32 s4, 0x2c0
	s_addc_u32 s5, s5, 0
	s_cmp_ge_u32 s4, 0x580
	s_addc_u32 s5, s5, 0
	s_cmp_ge_u32 s4, 0x840
	s_addc_u32 s5, s5, 0
	s_cmp_ge_u32 s4, 0xb00
	s_addc_u32 s5, s5, 0
	s_cmp_ge_u32 s4, 0xdc0
	s_addc_u32 s5, s5, 0
	s_cmp_ge_u32 s4, 0x1080
	s_addc_u32 s5, s5, 0
	s_cmp_ge_u32 s4, 0x13c0
	s_addc_u32 s5, s5, 0
	s_mul_i32 s12, s5, 0x2c0
	s_cmp_eq_u32 s5, 7
	s_cselect_b32 s13, 0x80, 0
	s_add_i32 s12, s12, s13
	s_sub_i32 s6, s4, s12
	s_cmp_eq_u32 s5, 2
	s_cselect_b32 s14, 1, 0
	s_cmp_eq_u32 s5, 5
	s_cselect_b32 s14, 1, s14
	s_mul_i32 s12, s6, 0x5d2
	s_lshr_b32 s12, s12, 16
	s_mul_i32 s15, s12, 44
	s_sub_i32 s15, s6, s15
	s_lshr_b32 s13, s6, 4
	s_and_b32 s8, s6, 15
	s_cmp_eq_u32 s14, 1
	s_cselect_b32 s7, s12, s13
	s_cselect_b32 s8, s15, s8
	s_movk_i32 s10, 0x400
	s_cselect_b32 s10, 0xb00, s10
	s_movk_i32 s9, 0xb00
	s_cselect_b32 s9, 0x400, s9
	s_cmp_eq_u32 s5, 7
	s_cselect_b32 s9, 0x400, s9
	s_cmp_eq_u32 s5, 6
	s_cselect_b32 s9, 0xd00, s9
	s_lshl_b32 s12, s7, 6
	s_lshr_b32 s13, s7, 1
	s_lshl_b32 s13, s13, 8
	s_and_b32 s15, s7, 1
	s_lshl_b32 s15, s15, 6
	s_add_i32 s13, s13, s15
	s_and_b32 s15, s5, 1
	s_cmp_eq_u32 s5, 1
	s_cselect_b32 s15, 0x80, 0
	s_cmp_eq_u32 s5, 4
	s_cselect_b32 s15, 0x80, s15
	s_add_i32 s13, s13, s15
	s_cmp_eq_u32 s9, 0xb00
	s_cselect_b32 s12, s13, s12
	s_mov_b32 s14, 0x30000
	s_cmp_eq_u32 s5, 1
	s_cselect_b32 s14, 0x30000, s14
	s_cmp_eq_u32 s5, 2
	s_cselect_b32 s14, 0xb30000, s14
	s_cmp_eq_u32 s5, 3
	s_cselect_b32 s14, 0x10b0000, s14
	s_cmp_eq_u32 s5, 4
	s_cselect_b32 s14, 0x10b0000, s14
	s_cmp_eq_u32 s5, 5
	s_cselect_b32 s14, 0x1bb0000, s14
	s_cmp_eq_u32 s5, 6
	s_cselect_b32 s14, 0x2130000, s14
	s_cmp_eq_u32 s5, 7
	s_cselect_b32 s14, 0x28f0000, s14
	s_cmp_eq_u32 s5, 6
	s_cselect_b32 s15, 1, 0
	s_cmp_ge_u32 s7, 24
	s_cselect_b32 s13, s15, 0
	s_cmp_eq_u32 s13, 1
	s_cselect_b32 s14, 0x2430000, s14
	s_cselect_b32 s13, 0x600, 0
	s_sub_i32 s12, s12, s13
	s_mul_i32 s12, s12, s10
	s_lshl_b32 s13, s8, 6
	s_add_i32 s12, s12, s13
	s_lshl_b32 s12, s12, 1
	s_add_u32 s12, s12, s14
	s_add_u32 s20, s30, s12
	s_addc_u32 s21, s31, 0
	v_mul_u32_u24_e32 v71, s10, v66
	v_add_lshl_u32 v71, v71, v67, 1
	ds_read_b32 v104, v69
	ds_read_b32 v105, v69 offset:260
	ds_read_b32 v106, v69 offset:520
	ds_read_b32 v107, v69 offset:780
	ds_read_b32 v108, v69 offset:1040
	ds_read_b32 v109, v69 offset:1300
	ds_read_b32 v110, v69 offset:1560
	ds_read_b32 v111, v69 offset:1820
	s_waitcnt lgkmcnt(0)
	v_cvt_pk_bf16_f32 v112, v104, v105
	v_cvt_pk_bf16_f32 v113, v106, v107
	v_cvt_pk_bf16_f32 v114, v108, v109
	v_cvt_pk_bf16_f32 v115, v110, v111
	global_store_dwordx4 v71, v[112:115], s[20:21]
	s_barrier
	s_add_i32 s4, s2, 0x800
	s_mov_b32 s5, 0
	s_cmp_ge_u32 s4, 0x2c0
	s_addc_u32 s5, s5, 0
	s_cmp_ge_u32 s4, 0x580
	s_addc_u32 s5, s5, 0
	s_cmp_ge_u32 s4, 0x840
	s_addc_u32 s5, s5, 0
	s_cmp_ge_u32 s4, 0xb00
	s_addc_u32 s5, s5, 0
	s_cmp_ge_u32 s4, 0xdc0
	s_addc_u32 s5, s5, 0
	s_cmp_ge_u32 s4, 0x1080
	s_addc_u32 s5, s5, 0
	s_cmp_ge_u32 s4, 0x13c0
	s_addc_u32 s5, s5, 0
	s_mul_i32 s12, s5, 0x2c0
	s_cmp_eq_u32 s5, 7
	s_cselect_b32 s13, 0x80, 0
	s_add_i32 s12, s12, s13
	s_sub_i32 s6, s4, s12
	s_cmp_eq_u32 s5, 2
	s_cselect_b32 s14, 1, 0
	s_cmp_eq_u32 s5, 5
	s_cselect_b32 s14, 1, s14
	s_mul_i32 s12, s6, 0x5d2
	s_lshr_b32 s12, s12, 16
	s_mul_i32 s15, s12, 44
	s_sub_i32 s15, s6, s15
	s_lshr_b32 s13, s6, 4
	s_and_b32 s8, s6, 15
	s_cmp_eq_u32 s14, 1
	s_cselect_b32 s7, s12, s13
	s_cselect_b32 s8, s15, s8
	s_movk_i32 s10, 0x400
	s_cselect_b32 s10, 0xb00, s10
	s_movk_i32 s9, 0xb00
	s_cselect_b32 s9, 0x400, s9
	s_cmp_eq_u32 s5, 7
	s_cselect_b32 s9, 0x400, s9
	s_cmp_eq_u32 s5, 6
	s_cselect_b32 s9, 0xd00, s9
	s_lshl_b32 s12, s5, 3
	s_lshr_b64 s[12:13], s[22:23], s12
	s_and_b32 s12, s12, 0xff
	s_add_i32 s13, s12, 1
	v_readlane_b32 s16, v241, s12
	v_readlane_b32 s17, v241, s13
	v_mul_u32_u24_e32 v70, s9, v65
	s_mul_i32 s14, s8, s9
	s_add_i32 s14, s14, s7
	s_lshl_b32 s14, s14, 8
	v_add_lshl_u32 v70, v70, v64, 2
	s_add_u32 s18, s16, s14
	s_addc_u32 s19, s17, 0
	s_lshl_b32 s15, s9, 5
	global_load_dword v72, v70, s[18:19]
	s_add_u32 s18, s18, s15
	s_addc_u32 s19, s19, 0
	global_load_dword v73, v70, s[18:19]
	s_add_u32 s18, s18, s15
	s_addc_u32 s19, s19, 0
	global_load_dword v74, v70, s[18:19]
	s_add_u32 s18, s18, s15
	s_addc_u32 s19, s19, 0
	global_load_dword v75, v70, s[18:19]
	s_add_u32 s18, s18, s15
	s_addc_u32 s19, s19, 0
	global_load_dword v76, v70, s[18:19]
	s_add_u32 s18, s18, s15
	s_addc_u32 s19, s19, 0
	global_load_dword v77, v70, s[18:19]
	s_add_u32 s18, s18, s15
	s_addc_u32 s19, s19, 0
	global_load_dword v78, v70, s[18:19]
	s_add_u32 s18, s18, s15
	s_addc_u32 s19, s19, 0
	global_load_dword v79, v70, s[18:19]
	s_waitcnt vmcnt(27)
	ds_write_b32 v68, v80
	ds_write_b32 v68, v81 offset:2080
	ds_write_b32 v68, v82 offset:4160
	ds_write_b32 v68, v83 offset:6240
	ds_write_b32 v68, v84 offset:8320
	ds_write_b32 v68, v85 offset:10400
	ds_write_b32 v68, v86 offset:12480
	ds_write_b32 v68, v87 offset:14560
	s_waitcnt lgkmcnt(0)
	s_barrier
	s_add_i32 s4, s2, 0x500
	s_mov_b32 s5, 0
	s_cmp_ge_u32 s4, 0x2c0
	s_addc_u32 s5, s5, 0
	s_cmp_ge_u32 s4, 0x580
	s_addc_u32 s5, s5, 0
	s_cmp_ge_u32 s4, 0x840
	s_addc_u32 s5, s5, 0
	s_cmp_ge_u32 s4, 0xb00
	s_addc_u32 s5, s5, 0
	s_cmp_ge_u32 s4, 0xdc0
	s_addc_u32 s5, s5, 0
	s_cmp_ge_u32 s4, 0x1080
	s_addc_u32 s5, s5, 0
	s_cmp_ge_u32 s4, 0x13c0
	s_addc_u32 s5, s5, 0
	s_mul_i32 s12, s5, 0x2c0
	s_cmp_eq_u32 s5, 7
	s_cselect_b32 s13, 0x80, 0
	s_add_i32 s12, s12, s13
	s_sub_i32 s6, s4, s12
	s_cmp_eq_u32 s5, 2
	s_cselect_b32 s14, 1, 0
	s_cmp_eq_u32 s5, 5
	s_cselect_b32 s14, 1, s14
	s_mul_i32 s12, s6, 0x5d2
	s_lshr_b32 s12, s12, 16
	s_mul_i32 s15, s12, 44
	s_sub_i32 s15, s6, s15
	s_lshr_b32 s13, s6, 4
	s_and_b32 s8, s6, 15
	s_cmp_eq_u32 s14, 1
	s_cselect_b32 s7, s12, s13
	s_cselect_b32 s8, s15, s8
	s_movk_i32 s10, 0x400
	s_cselect_b32 s10, 0xb00, s10
	s_movk_i32 s9, 0xb00
	s_cselect_b32 s9, 0x400, s9
	s_cmp_eq_u32 s5, 7
	s_cselect_b32 s9, 0x400, s9
	s_cmp_eq_u32 s5, 6
	s_cselect_b32 s9, 0xd00, s9
	s_lshl_b32 s12, s7, 6
	s_lshr_b32 s13, s7, 1
	s_lshl_b32 s13, s13, 8
	s_and_b32 s15, s7, 1
	s_lshl_b32 s15, s15, 6
	s_add_i32 s13, s13, s15
	s_and_b32 s15, s5, 1
	s_cmp_eq_u32 s5, 1
	s_cselect_b32 s15, 0x80, 0
	s_cmp_eq_u32 s5, 4
	s_cselect_b32 s15, 0x80, s15
	s_add_i32 s13, s13, s15
	s_cmp_eq_u32 s9, 0xb00
	s_cselect_b32 s12, s13, s12
	s_mov_b32 s14, 0x30000
	s_cmp_eq_u32 s5, 1
	s_cselect_b32 s14, 0x30000, s14
	s_cmp_eq_u32 s5, 2
	s_cselect_b32 s14, 0xb30000, s14
	s_cmp_eq_u32 s5, 3
	s_cselect_b32 s14, 0x10b0000, s14
	s_cmp_eq_u32 s5, 4
	s_cselect_b32 s14, 0x10b0000, s14
	s_cmp_eq_u32 s5, 5
	s_cselect_b32 s14, 0x1bb0000, s14
	s_cmp_eq_u32 s5, 6
	s_cselect_b32 s14, 0x2130000, s14
	s_cmp_eq_u32 s5, 7
	s_cselect_b32 s14, 0x28f0000, s14
	s_cmp_eq_u32 s5, 6
	s_cselect_b32 s15, 1, 0
	s_cmp_ge_u32 s7, 24
	s_cselect_b32 s13, s15, 0
	s_cmp_eq_u32 s13, 1
	s_cselect_b32 s14, 0x2430000, s14
	s_cselect_b32 s13, 0x600, 0
	s_sub_i32 s12, s12, s13
	s_mul_i32 s12, s12, s10
	s_lshl_b32 s13, s8, 6
	s_add_i32 s12, s12, s13
	s_lshl_b32 s12, s12, 1
	s_add_u32 s12, s12, s14
	s_add_u32 s20, s30, s12
	s_addc_u32 s21, s31, 0
	v_mul_u32_u24_e32 v71, s10, v66
	v_add_lshl_u32 v71, v71, v67, 1
	ds_read_b32 v104, v69
	ds_read_b32 v105, v69 offset:260
	ds_read_b32 v106, v69 offset:520
	ds_read_b32 v107, v69 offset:780
	ds_read_b32 v108, v69 offset:1040
	ds_read_b32 v109, v69 offset:1300
	ds_read_b32 v110, v69 offset:1560
	ds_read_b32 v111, v69 offset:1820
	s_waitcnt lgkmcnt(0)
	v_cvt_pk_bf16_f32 v116, v104, v105
	v_cvt_pk_bf16_f32 v117, v106, v107
	v_cvt_pk_bf16_f32 v118, v108, v109
	v_cvt_pk_bf16_f32 v119, v110, v111
	global_store_dwordx4 v71, v[116:119], s[20:21]
	s_barrier
	s_add_i32 s4, s2, 0x900
	s_mov_b32 s5, 0
	s_cmp_ge_u32 s4, 0x2c0
	s_addc_u32 s5, s5, 0
	s_cmp_ge_u32 s4, 0x580
	s_addc_u32 s5, s5, 0
	s_cmp_ge_u32 s4, 0x840
	s_addc_u32 s5, s5, 0
	s_cmp_ge_u32 s4, 0xb00
	s_addc_u32 s5, s5, 0
	s_cmp_ge_u32 s4, 0xdc0
	s_addc_u32 s5, s5, 0
	s_cmp_ge_u32 s4, 0x1080
	s_addc_u32 s5, s5, 0
	s_cmp_ge_u32 s4, 0x13c0
	s_addc_u32 s5, s5, 0
	s_mul_i32 s12, s5, 0x2c0
	s_cmp_eq_u32 s5, 7
	s_cselect_b32 s13, 0x80, 0
	s_add_i32 s12, s12, s13
	s_sub_i32 s6, s4, s12
	s_cmp_eq_u32 s5, 2
	s_cselect_b32 s14, 1, 0
	s_cmp_eq_u32 s5, 5
	s_cselect_b32 s14, 1, s14
	s_mul_i32 s12, s6, 0x5d2
	s_lshr_b32 s12, s12, 16
	s_mul_i32 s15, s12, 44
	s_sub_i32 s15, s6, s15
	s_lshr_b32 s13, s6, 4
	s_and_b32 s8, s6, 15
	s_cmp_eq_u32 s14, 1
	s_cselect_b32 s7, s12, s13
	s_cselect_b32 s8, s15, s8
	s_movk_i32 s10, 0x400
	s_cselect_b32 s10, 0xb00, s10
	s_movk_i32 s9, 0xb00
	s_cselect_b32 s9, 0x400, s9
	s_cmp_eq_u32 s5, 7
	s_cselect_b32 s9, 0x400, s9
	s_cmp_eq_u32 s5, 6
	s_cselect_b32 s9, 0xd00, s9
	s_lshl_b32 s12, s5, 3
	s_lshr_b64 s[12:13], s[22:23], s12
	s_and_b32 s12, s12, 0xff
	s_add_i32 s13, s12, 1
	v_readlane_b32 s16, v241, s12
	v_readlane_b32 s17, v241, s13
	v_mul_u32_u24_e32 v70, s9, v65
	s_mul_i32 s14, s8, s9
	s_add_i32 s14, s14, s7
	s_lshl_b32 s14, s14, 8
	v_add_lshl_u32 v70, v70, v64, 2
	s_add_u32 s18, s16, s14
	s_addc_u32 s19, s17, 0
	s_lshl_b32 s15, s9, 5
	global_load_dword v80, v70, s[18:19]
	s_add_u32 s18, s18, s15
	s_addc_u32 s19, s19, 0
	global_load_dword v81, v70, s[18:19]
	s_add_u32 s18, s18, s15
	s_addc_u32 s19, s19, 0
	global_load_dword v82, v70, s[18:19]
	s_add_u32 s18, s18, s15
	s_addc_u32 s19, s19, 0
	global_load_dword v83, v70, s[18:19]
	s_add_u32 s18, s18, s15
	s_addc_u32 s19, s19, 0
	global_load_dword v84, v70, s[18:19]
	s_add_u32 s18, s18, s15
	s_addc_u32 s19, s19, 0
	global_load_dword v85, v70, s[18:19]
	s_add_u32 s18, s18, s15
	s_addc_u32 s19, s19, 0
	global_load_dword v86, v70, s[18:19]
	s_add_u32 s18, s18, s15
	s_addc_u32 s19, s19, 0
	global_load_dword v87, v70, s[18:19]
	s_waitcnt vmcnt(27)
	ds_write_b32 v68, v88
	ds_write_b32 v68, v89 offset:2080
	ds_write_b32 v68, v90 offset:4160
	ds_write_b32 v68, v91 offset:6240
	ds_write_b32 v68, v92 offset:8320
	ds_write_b32 v68, v93 offset:10400
	ds_write_b32 v68, v94 offset:12480
	ds_write_b32 v68, v95 offset:14560
	s_waitcnt lgkmcnt(0)
	s_barrier
	s_add_i32 s4, s2, 0x600
	s_mov_b32 s5, 0
	s_cmp_ge_u32 s4, 0x2c0
	s_addc_u32 s5, s5, 0
	s_cmp_ge_u32 s4, 0x580
	s_addc_u32 s5, s5, 0
	s_cmp_ge_u32 s4, 0x840
	s_addc_u32 s5, s5, 0
	s_cmp_ge_u32 s4, 0xb00
	s_addc_u32 s5, s5, 0
	s_cmp_ge_u32 s4, 0xdc0
	s_addc_u32 s5, s5, 0
	s_cmp_ge_u32 s4, 0x1080
	s_addc_u32 s5, s5, 0
	s_cmp_ge_u32 s4, 0x13c0
	s_addc_u32 s5, s5, 0
	s_mul_i32 s12, s5, 0x2c0
	s_cmp_eq_u32 s5, 7
	s_cselect_b32 s13, 0x80, 0
	s_add_i32 s12, s12, s13
	s_sub_i32 s6, s4, s12
	s_cmp_eq_u32 s5, 2
	s_cselect_b32 s14, 1, 0
	s_cmp_eq_u32 s5, 5
	s_cselect_b32 s14, 1, s14
	s_mul_i32 s12, s6, 0x5d2
	s_lshr_b32 s12, s12, 16
	s_mul_i32 s15, s12, 44
	s_sub_i32 s15, s6, s15
	s_lshr_b32 s13, s6, 4
	s_and_b32 s8, s6, 15
	s_cmp_eq_u32 s14, 1
	s_cselect_b32 s7, s12, s13
	s_cselect_b32 s8, s15, s8
	s_movk_i32 s10, 0x400
	s_cselect_b32 s10, 0xb00, s10
	s_movk_i32 s9, 0xb00
	s_cselect_b32 s9, 0x400, s9
	s_cmp_eq_u32 s5, 7
	s_cselect_b32 s9, 0x400, s9
	s_cmp_eq_u32 s5, 6
	s_cselect_b32 s9, 0xd00, s9
	s_lshl_b32 s12, s7, 6
	s_lshr_b32 s13, s7, 1
	s_lshl_b32 s13, s13, 8
	s_and_b32 s15, s7, 1
	s_lshl_b32 s15, s15, 6
	s_add_i32 s13, s13, s15
	s_and_b32 s15, s5, 1
	s_cmp_eq_u32 s5, 1
	s_cselect_b32 s15, 0x80, 0
	s_cmp_eq_u32 s5, 4
	s_cselect_b32 s15, 0x80, s15
	s_add_i32 s13, s13, s15
	s_cmp_eq_u32 s9, 0xb00
	s_cselect_b32 s12, s13, s12
	s_mov_b32 s14, 0x30000
	s_cmp_eq_u32 s5, 1
	s_cselect_b32 s14, 0x30000, s14
	s_cmp_eq_u32 s5, 2
	s_cselect_b32 s14, 0xb30000, s14
	s_cmp_eq_u32 s5, 3
	s_cselect_b32 s14, 0x10b0000, s14
	s_cmp_eq_u32 s5, 4
	s_cselect_b32 s14, 0x10b0000, s14
	s_cmp_eq_u32 s5, 5
	s_cselect_b32 s14, 0x1bb0000, s14
	s_cmp_eq_u32 s5, 6
	s_cselect_b32 s14, 0x2130000, s14
	s_cmp_eq_u32 s5, 7
	s_cselect_b32 s14, 0x28f0000, s14
	s_cmp_eq_u32 s5, 6
	s_cselect_b32 s15, 1, 0
	s_cmp_ge_u32 s7, 24
	s_cselect_b32 s13, s15, 0
	s_cmp_eq_u32 s13, 1
	s_cselect_b32 s14, 0x2430000, s14
	s_cselect_b32 s13, 0x600, 0
	s_sub_i32 s12, s12, s13
	s_mul_i32 s12, s12, s10
	s_lshl_b32 s13, s8, 6
	s_add_i32 s12, s12, s13
	s_lshl_b32 s12, s12, 1
	s_add_u32 s12, s12, s14
	s_add_u32 s20, s30, s12
	s_addc_u32 s21, s31, 0
	v_mul_u32_u24_e32 v71, s10, v66
	v_add_lshl_u32 v71, v71, v67, 1
	ds_read_b32 v104, v69
	ds_read_b32 v105, v69 offset:260
	ds_read_b32 v106, v69 offset:520
	ds_read_b32 v107, v69 offset:780
	ds_read_b32 v108, v69 offset:1040
	ds_read_b32 v109, v69 offset:1300
	ds_read_b32 v110, v69 offset:1560
	ds_read_b32 v111, v69 offset:1820
	s_waitcnt lgkmcnt(0)
	v_cvt_pk_bf16_f32 v112, v104, v105
	v_cvt_pk_bf16_f32 v113, v106, v107
	v_cvt_pk_bf16_f32 v114, v108, v109
	v_cvt_pk_bf16_f32 v115, v110, v111
	global_store_dwordx4 v71, v[112:115], s[20:21]
	s_barrier
	s_add_i32 s4, s2, 0xa00
	s_mov_b32 s5, 0
	s_cmp_ge_u32 s4, 0x2c0
	s_addc_u32 s5, s5, 0
	s_cmp_ge_u32 s4, 0x580
	s_addc_u32 s5, s5, 0
	s_cmp_ge_u32 s4, 0x840
	s_addc_u32 s5, s5, 0
	s_cmp_ge_u32 s4, 0xb00
	s_addc_u32 s5, s5, 0
	s_cmp_ge_u32 s4, 0xdc0
	s_addc_u32 s5, s5, 0
	s_cmp_ge_u32 s4, 0x1080
	s_addc_u32 s5, s5, 0
	s_cmp_ge_u32 s4, 0x13c0
	s_addc_u32 s5, s5, 0
	s_mul_i32 s12, s5, 0x2c0
	s_cmp_eq_u32 s5, 7
	s_cselect_b32 s13, 0x80, 0
	s_add_i32 s12, s12, s13
	s_sub_i32 s6, s4, s12
	s_cmp_eq_u32 s5, 2
	s_cselect_b32 s14, 1, 0
	s_cmp_eq_u32 s5, 5
	s_cselect_b32 s14, 1, s14
	s_mul_i32 s12, s6, 0x5d2
	s_lshr_b32 s12, s12, 16
	s_mul_i32 s15, s12, 44
	s_sub_i32 s15, s6, s15
	s_lshr_b32 s13, s6, 4
	s_and_b32 s8, s6, 15
	s_cmp_eq_u32 s14, 1
	s_cselect_b32 s7, s12, s13
	s_cselect_b32 s8, s15, s8
	s_movk_i32 s10, 0x400
	s_cselect_b32 s10, 0xb00, s10
	s_movk_i32 s9, 0xb00
	s_cselect_b32 s9, 0x400, s9
	s_cmp_eq_u32 s5, 7
	s_cselect_b32 s9, 0x400, s9
	s_cmp_eq_u32 s5, 6
	s_cselect_b32 s9, 0xd00, s9
	s_lshl_b32 s12, s5, 3
	s_lshr_b64 s[12:13], s[22:23], s12
	s_and_b32 s12, s12, 0xff
	s_add_i32 s13, s12, 1
	v_readlane_b32 s16, v241, s12
	v_readlane_b32 s17, v241, s13
	v_mul_u32_u24_e32 v70, s9, v65
	s_mul_i32 s14, s8, s9
	s_add_i32 s14, s14, s7
	s_lshl_b32 s14, s14, 8
	v_add_lshl_u32 v70, v70, v64, 2
	s_add_u32 s18, s16, s14
	s_addc_u32 s19, s17, 0
	s_lshl_b32 s15, s9, 5
	global_load_dword v88, v70, s[18:19]
	s_add_u32 s18, s18, s15
	s_addc_u32 s19, s19, 0
	global_load_dword v89, v70, s[18:19]
	s_add_u32 s18, s18, s15
	s_addc_u32 s19, s19, 0
	global_load_dword v90, v70, s[18:19]
	s_add_u32 s18, s18, s15
	s_addc_u32 s19, s19, 0
	global_load_dword v91, v70, s[18:19]
	s_add_u32 s18, s18, s15
	s_addc_u32 s19, s19, 0
	global_load_dword v92, v70, s[18:19]
	s_add_u32 s18, s18, s15
	s_addc_u32 s19, s19, 0
	global_load_dword v93, v70, s[18:19]
	s_add_u32 s18, s18, s15
	s_addc_u32 s19, s19, 0
	global_load_dword v94, v70, s[18:19]
	s_add_u32 s18, s18, s15
	s_addc_u32 s19, s19, 0
	global_load_dword v95, v70, s[18:19]
	s_waitcnt vmcnt(27)
	ds_write_b32 v68, v96
	ds_write_b32 v68, v97 offset:2080
	ds_write_b32 v68, v98 offset:4160
	ds_write_b32 v68, v99 offset:6240
	ds_write_b32 v68, v100 offset:8320
	ds_write_b32 v68, v101 offset:10400
	ds_write_b32 v68, v102 offset:12480
	ds_write_b32 v68, v103 offset:14560
	s_waitcnt lgkmcnt(0)
	s_barrier
	s_add_i32 s4, s2, 0x700
	s_mov_b32 s5, 0
	s_cmp_ge_u32 s4, 0x2c0
	s_addc_u32 s5, s5, 0
	s_cmp_ge_u32 s4, 0x580
	s_addc_u32 s5, s5, 0
	s_cmp_ge_u32 s4, 0x840
	s_addc_u32 s5, s5, 0
	s_cmp_ge_u32 s4, 0xb00
	s_addc_u32 s5, s5, 0
	s_cmp_ge_u32 s4, 0xdc0
	s_addc_u32 s5, s5, 0
	s_cmp_ge_u32 s4, 0x1080
	s_addc_u32 s5, s5, 0
	s_cmp_ge_u32 s4, 0x13c0
	s_addc_u32 s5, s5, 0
	s_mul_i32 s12, s5, 0x2c0
	s_cmp_eq_u32 s5, 7
	s_cselect_b32 s13, 0x80, 0
	s_add_i32 s12, s12, s13
	s_sub_i32 s6, s4, s12
	s_cmp_eq_u32 s5, 2
	s_cselect_b32 s14, 1, 0
	s_cmp_eq_u32 s5, 5
	s_cselect_b32 s14, 1, s14
	s_mul_i32 s12, s6, 0x5d2
	s_lshr_b32 s12, s12, 16
	s_mul_i32 s15, s12, 44
	s_sub_i32 s15, s6, s15
	s_lshr_b32 s13, s6, 4
	s_and_b32 s8, s6, 15
	s_cmp_eq_u32 s14, 1
	s_cselect_b32 s7, s12, s13
	s_cselect_b32 s8, s15, s8
	s_movk_i32 s10, 0x400
	s_cselect_b32 s10, 0xb00, s10
	s_movk_i32 s9, 0xb00
	s_cselect_b32 s9, 0x400, s9
	s_cmp_eq_u32 s5, 7
	s_cselect_b32 s9, 0x400, s9
	s_cmp_eq_u32 s5, 6
	s_cselect_b32 s9, 0xd00, s9
	s_lshl_b32 s12, s7, 6
	s_lshr_b32 s13, s7, 1
	s_lshl_b32 s13, s13, 8
	s_and_b32 s15, s7, 1
	s_lshl_b32 s15, s15, 6
	s_add_i32 s13, s13, s15
	s_and_b32 s15, s5, 1
	s_cmp_eq_u32 s5, 1
	s_cselect_b32 s15, 0x80, 0
	s_cmp_eq_u32 s5, 4
	s_cselect_b32 s15, 0x80, s15
	s_add_i32 s13, s13, s15
	s_cmp_eq_u32 s9, 0xb00
	s_cselect_b32 s12, s13, s12
	s_mov_b32 s14, 0x30000
	s_cmp_eq_u32 s5, 1
	s_cselect_b32 s14, 0x30000, s14
	s_cmp_eq_u32 s5, 2
	s_cselect_b32 s14, 0xb30000, s14
	s_cmp_eq_u32 s5, 3
	s_cselect_b32 s14, 0x10b0000, s14
	s_cmp_eq_u32 s5, 4
	s_cselect_b32 s14, 0x10b0000, s14
	s_cmp_eq_u32 s5, 5
	s_cselect_b32 s14, 0x1bb0000, s14
	s_cmp_eq_u32 s5, 6
	s_cselect_b32 s14, 0x2130000, s14
	s_cmp_eq_u32 s5, 7
	s_cselect_b32 s14, 0x28f0000, s14
	s_cmp_eq_u32 s5, 6
	s_cselect_b32 s15, 1, 0
	s_cmp_ge_u32 s7, 24
	s_cselect_b32 s13, s15, 0
	s_cmp_eq_u32 s13, 1
	s_cselect_b32 s14, 0x2430000, s14
	s_cselect_b32 s13, 0x600, 0
	s_sub_i32 s12, s12, s13
	s_mul_i32 s12, s12, s10
	s_lshl_b32 s13, s8, 6
	s_add_i32 s12, s12, s13
	s_lshl_b32 s12, s12, 1
	s_add_u32 s12, s12, s14
	s_add_u32 s20, s30, s12
	s_addc_u32 s21, s31, 0
	v_mul_u32_u24_e32 v71, s10, v66
	v_add_lshl_u32 v71, v71, v67, 1
	ds_read_b32 v104, v69
	ds_read_b32 v105, v69 offset:260
	ds_read_b32 v106, v69 offset:520
	ds_read_b32 v107, v69 offset:780
	ds_read_b32 v108, v69 offset:1040
	ds_read_b32 v109, v69 offset:1300
	ds_read_b32 v110, v69 offset:1560
	ds_read_b32 v111, v69 offset:1820
	s_waitcnt lgkmcnt(0)
	v_cvt_pk_bf16_f32 v116, v104, v105
	v_cvt_pk_bf16_f32 v117, v106, v107
	v_cvt_pk_bf16_f32 v118, v108, v109
	v_cvt_pk_bf16_f32 v119, v110, v111
	global_store_dwordx4 v71, v[116:119], s[20:21]
	s_barrier
	s_add_i32 s4, s2, 0xb00
	s_mov_b32 s5, 0
	s_cmp_ge_u32 s4, 0x2c0
	s_addc_u32 s5, s5, 0
	s_cmp_ge_u32 s4, 0x580
	s_addc_u32 s5, s5, 0
	s_cmp_ge_u32 s4, 0x840
	s_addc_u32 s5, s5, 0
	s_cmp_ge_u32 s4, 0xb00
	s_addc_u32 s5, s5, 0
	s_cmp_ge_u32 s4, 0xdc0
	s_addc_u32 s5, s5, 0
	s_cmp_ge_u32 s4, 0x1080
	s_addc_u32 s5, s5, 0
	s_cmp_ge_u32 s4, 0x13c0
	s_addc_u32 s5, s5, 0
	s_mul_i32 s12, s5, 0x2c0
	s_cmp_eq_u32 s5, 7
	s_cselect_b32 s13, 0x80, 0
	s_add_i32 s12, s12, s13
	s_sub_i32 s6, s4, s12
	s_cmp_eq_u32 s5, 2
	s_cselect_b32 s14, 1, 0
	s_cmp_eq_u32 s5, 5
	s_cselect_b32 s14, 1, s14
	s_mul_i32 s12, s6, 0x5d2
	s_lshr_b32 s12, s12, 16
	s_mul_i32 s15, s12, 44
	s_sub_i32 s15, s6, s15
	s_lshr_b32 s13, s6, 4
	s_and_b32 s8, s6, 15
	s_cmp_eq_u32 s14, 1
	s_cselect_b32 s7, s12, s13
	s_cselect_b32 s8, s15, s8
	s_movk_i32 s10, 0x400
	s_cselect_b32 s10, 0xb00, s10
	s_movk_i32 s9, 0xb00
	s_cselect_b32 s9, 0x400, s9
	s_cmp_eq_u32 s5, 7
	s_cselect_b32 s9, 0x400, s9
	s_cmp_eq_u32 s5, 6
	s_cselect_b32 s9, 0xd00, s9
	s_lshl_b32 s12, s5, 3
	s_lshr_b64 s[12:13], s[22:23], s12
	s_and_b32 s12, s12, 0xff
	s_add_i32 s13, s12, 1
	v_readlane_b32 s16, v241, s12
	v_readlane_b32 s17, v241, s13
	v_mul_u32_u24_e32 v70, s9, v65
	s_mul_i32 s14, s8, s9
	s_add_i32 s14, s14, s7
	s_lshl_b32 s14, s14, 8
	v_add_lshl_u32 v70, v70, v64, 2
	s_add_u32 s18, s16, s14
	s_addc_u32 s19, s17, 0
	s_lshl_b32 s15, s9, 5
	global_load_dword v96, v70, s[18:19]
	s_add_u32 s18, s18, s15
	s_addc_u32 s19, s19, 0
	global_load_dword v97, v70, s[18:19]
	s_add_u32 s18, s18, s15
	s_addc_u32 s19, s19, 0
	global_load_dword v98, v70, s[18:19]
	s_add_u32 s18, s18, s15
	s_addc_u32 s19, s19, 0
	global_load_dword v99, v70, s[18:19]
	s_add_u32 s18, s18, s15
	s_addc_u32 s19, s19, 0
	global_load_dword v100, v70, s[18:19]
	s_add_u32 s18, s18, s15
	s_addc_u32 s19, s19, 0
	global_load_dword v101, v70, s[18:19]
	s_add_u32 s18, s18, s15
	s_addc_u32 s19, s19, 0
	global_load_dword v102, v70, s[18:19]
	s_add_u32 s18, s18, s15
	s_addc_u32 s19, s19, 0
	global_load_dword v103, v70, s[18:19]
	s_waitcnt vmcnt(27)
	ds_write_b32 v68, v72
	ds_write_b32 v68, v73 offset:2080
	ds_write_b32 v68, v74 offset:4160
	ds_write_b32 v68, v75 offset:6240
	ds_write_b32 v68, v76 offset:8320
	ds_write_b32 v68, v77 offset:10400
	ds_write_b32 v68, v78 offset:12480
	ds_write_b32 v68, v79 offset:14560
	s_waitcnt lgkmcnt(0)
	s_barrier
	s_add_i32 s4, s2, 0x800
	s_mov_b32 s5, 0
	s_cmp_ge_u32 s4, 0x2c0
	s_addc_u32 s5, s5, 0
	s_cmp_ge_u32 s4, 0x580
	s_addc_u32 s5, s5, 0
	s_cmp_ge_u32 s4, 0x840
	s_addc_u32 s5, s5, 0
	s_cmp_ge_u32 s4, 0xb00
	s_addc_u32 s5, s5, 0
	s_cmp_ge_u32 s4, 0xdc0
	s_addc_u32 s5, s5, 0
	s_cmp_ge_u32 s4, 0x1080
	s_addc_u32 s5, s5, 0
	s_cmp_ge_u32 s4, 0x13c0
	s_addc_u32 s5, s5, 0
	s_mul_i32 s12, s5, 0x2c0
	s_cmp_eq_u32 s5, 7
	s_cselect_b32 s13, 0x80, 0
	s_add_i32 s12, s12, s13
	s_sub_i32 s6, s4, s12
	s_cmp_eq_u32 s5, 2
	s_cselect_b32 s14, 1, 0
	s_cmp_eq_u32 s5, 5
	s_cselect_b32 s14, 1, s14
	s_mul_i32 s12, s6, 0x5d2
	s_lshr_b32 s12, s12, 16
	s_mul_i32 s15, s12, 44
	s_sub_i32 s15, s6, s15
	s_lshr_b32 s13, s6, 4
	s_and_b32 s8, s6, 15
	s_cmp_eq_u32 s14, 1
	s_cselect_b32 s7, s12, s13
	s_cselect_b32 s8, s15, s8
	s_movk_i32 s10, 0x400
	s_cselect_b32 s10, 0xb00, s10
	s_movk_i32 s9, 0xb00
	s_cselect_b32 s9, 0x400, s9
	s_cmp_eq_u32 s5, 7
	s_cselect_b32 s9, 0x400, s9
	s_cmp_eq_u32 s5, 6
	s_cselect_b32 s9, 0xd00, s9
	s_lshl_b32 s12, s7, 6
	s_lshr_b32 s13, s7, 1
	s_lshl_b32 s13, s13, 8
	s_and_b32 s15, s7, 1
	s_lshl_b32 s15, s15, 6
	s_add_i32 s13, s13, s15
	s_and_b32 s15, s5, 1
	s_cmp_eq_u32 s5, 1
	s_cselect_b32 s15, 0x80, 0
	s_cmp_eq_u32 s5, 4
	s_cselect_b32 s15, 0x80, s15
	s_add_i32 s13, s13, s15
	s_cmp_eq_u32 s9, 0xb00
	s_cselect_b32 s12, s13, s12
	s_mov_b32 s14, 0x30000
	s_cmp_eq_u32 s5, 1
	s_cselect_b32 s14, 0x30000, s14
	s_cmp_eq_u32 s5, 2
	s_cselect_b32 s14, 0xb30000, s14
	s_cmp_eq_u32 s5, 3
	s_cselect_b32 s14, 0x10b0000, s14
	s_cmp_eq_u32 s5, 4
	s_cselect_b32 s14, 0x10b0000, s14
	s_cmp_eq_u32 s5, 5
	s_cselect_b32 s14, 0x1bb0000, s14
	s_cmp_eq_u32 s5, 6
	s_cselect_b32 s14, 0x2130000, s14
	s_cmp_eq_u32 s5, 7
	s_cselect_b32 s14, 0x28f0000, s14
	s_cmp_eq_u32 s5, 6
	s_cselect_b32 s15, 1, 0
	s_cmp_ge_u32 s7, 24
	s_cselect_b32 s13, s15, 0
	s_cmp_eq_u32 s13, 1
	s_cselect_b32 s14, 0x2430000, s14
	s_cselect_b32 s13, 0x600, 0
	s_sub_i32 s12, s12, s13
	s_mul_i32 s12, s12, s10
	s_lshl_b32 s13, s8, 6
	s_add_i32 s12, s12, s13
	s_lshl_b32 s12, s12, 1
	s_add_u32 s12, s12, s14
	s_add_u32 s20, s30, s12
	s_addc_u32 s21, s31, 0
	v_mul_u32_u24_e32 v71, s10, v66
	v_add_lshl_u32 v71, v71, v67, 1
	ds_read_b32 v104, v69
	ds_read_b32 v105, v69 offset:260
	ds_read_b32 v106, v69 offset:520
	ds_read_b32 v107, v69 offset:780
	ds_read_b32 v108, v69 offset:1040
	ds_read_b32 v109, v69 offset:1300
	ds_read_b32 v110, v69 offset:1560
	ds_read_b32 v111, v69 offset:1820
	s_waitcnt lgkmcnt(0)
	v_cvt_pk_bf16_f32 v112, v104, v105
	v_cvt_pk_bf16_f32 v113, v106, v107
	v_cvt_pk_bf16_f32 v114, v108, v109
	v_cvt_pk_bf16_f32 v115, v110, v111
	global_store_dwordx4 v71, v[112:115], s[20:21]
	s_barrier
	s_add_i32 s4, s2, 0xc00
	s_mov_b32 s5, 0
	s_cmp_ge_u32 s4, 0x2c0
	s_addc_u32 s5, s5, 0
	s_cmp_ge_u32 s4, 0x580
	s_addc_u32 s5, s5, 0
	s_cmp_ge_u32 s4, 0x840
	s_addc_u32 s5, s5, 0
	s_cmp_ge_u32 s4, 0xb00
	s_addc_u32 s5, s5, 0
	s_cmp_ge_u32 s4, 0xdc0
	s_addc_u32 s5, s5, 0
	s_cmp_ge_u32 s4, 0x1080
	s_addc_u32 s5, s5, 0
	s_cmp_ge_u32 s4, 0x13c0
	s_addc_u32 s5, s5, 0
	s_mul_i32 s12, s5, 0x2c0
	s_cmp_eq_u32 s5, 7
	s_cselect_b32 s13, 0x80, 0
	s_add_i32 s12, s12, s13
	s_sub_i32 s6, s4, s12
	s_cmp_eq_u32 s5, 2
	s_cselect_b32 s14, 1, 0
	s_cmp_eq_u32 s5, 5
	s_cselect_b32 s14, 1, s14
	s_mul_i32 s12, s6, 0x5d2
	s_lshr_b32 s12, s12, 16
	s_mul_i32 s15, s12, 44
	s_sub_i32 s15, s6, s15
	s_lshr_b32 s13, s6, 4
	s_and_b32 s8, s6, 15
	s_cmp_eq_u32 s14, 1
	s_cselect_b32 s7, s12, s13
	s_cselect_b32 s8, s15, s8
	s_movk_i32 s10, 0x400
	s_cselect_b32 s10, 0xb00, s10
	s_movk_i32 s9, 0xb00
	s_cselect_b32 s9, 0x400, s9
	s_cmp_eq_u32 s5, 7
	s_cselect_b32 s9, 0x400, s9
	s_cmp_eq_u32 s5, 6
	s_cselect_b32 s9, 0xd00, s9
	s_lshl_b32 s12, s5, 3
	s_lshr_b64 s[12:13], s[22:23], s12
	s_and_b32 s12, s12, 0xff
	s_add_i32 s13, s12, 1
	v_readlane_b32 s16, v241, s12
	v_readlane_b32 s17, v241, s13
	v_mul_u32_u24_e32 v70, s9, v65
	s_mul_i32 s14, s8, s9
	s_add_i32 s14, s14, s7
	s_lshl_b32 s14, s14, 8
	v_add_lshl_u32 v70, v70, v64, 2
	s_add_u32 s18, s16, s14
	s_addc_u32 s19, s17, 0
	s_lshl_b32 s15, s9, 5
	global_load_dword v72, v70, s[18:19]
	s_add_u32 s18, s18, s15
	s_addc_u32 s19, s19, 0
	global_load_dword v73, v70, s[18:19]
	s_add_u32 s18, s18, s15
	s_addc_u32 s19, s19, 0
	global_load_dword v74, v70, s[18:19]
	s_add_u32 s18, s18, s15
	s_addc_u32 s19, s19, 0
	global_load_dword v75, v70, s[18:19]
	s_add_u32 s18, s18, s15
	s_addc_u32 s19, s19, 0
	global_load_dword v76, v70, s[18:19]
	s_add_u32 s18, s18, s15
	s_addc_u32 s19, s19, 0
	global_load_dword v77, v70, s[18:19]
	s_add_u32 s18, s18, s15
	s_addc_u32 s19, s19, 0
	global_load_dword v78, v70, s[18:19]
	s_add_u32 s18, s18, s15
	s_addc_u32 s19, s19, 0
	global_load_dword v79, v70, s[18:19]
	s_waitcnt vmcnt(27)
	ds_write_b32 v68, v80
	ds_write_b32 v68, v81 offset:2080
	ds_write_b32 v68, v82 offset:4160
	ds_write_b32 v68, v83 offset:6240
	ds_write_b32 v68, v84 offset:8320
	ds_write_b32 v68, v85 offset:10400
	ds_write_b32 v68, v86 offset:12480
	ds_write_b32 v68, v87 offset:14560
	s_waitcnt lgkmcnt(0)
	s_barrier
	s_add_i32 s4, s2, 0x900
	s_mov_b32 s5, 0
	s_cmp_ge_u32 s4, 0x2c0
	s_addc_u32 s5, s5, 0
	s_cmp_ge_u32 s4, 0x580
	s_addc_u32 s5, s5, 0
	s_cmp_ge_u32 s4, 0x840
	s_addc_u32 s5, s5, 0
	s_cmp_ge_u32 s4, 0xb00
	s_addc_u32 s5, s5, 0
	s_cmp_ge_u32 s4, 0xdc0
	s_addc_u32 s5, s5, 0
	s_cmp_ge_u32 s4, 0x1080
	s_addc_u32 s5, s5, 0
	s_cmp_ge_u32 s4, 0x13c0
	s_addc_u32 s5, s5, 0
	s_mul_i32 s12, s5, 0x2c0
	s_cmp_eq_u32 s5, 7
	s_cselect_b32 s13, 0x80, 0
	s_add_i32 s12, s12, s13
	s_sub_i32 s6, s4, s12
	s_cmp_eq_u32 s5, 2
	s_cselect_b32 s14, 1, 0
	s_cmp_eq_u32 s5, 5
	s_cselect_b32 s14, 1, s14
	s_mul_i32 s12, s6, 0x5d2
	s_lshr_b32 s12, s12, 16
	s_mul_i32 s15, s12, 44
	s_sub_i32 s15, s6, s15
	s_lshr_b32 s13, s6, 4
	s_and_b32 s8, s6, 15
	s_cmp_eq_u32 s14, 1
	s_cselect_b32 s7, s12, s13
	s_cselect_b32 s8, s15, s8
	s_movk_i32 s10, 0x400
	s_cselect_b32 s10, 0xb00, s10
	s_movk_i32 s9, 0xb00
	s_cselect_b32 s9, 0x400, s9
	s_cmp_eq_u32 s5, 7
	s_cselect_b32 s9, 0x400, s9
	s_cmp_eq_u32 s5, 6
	s_cselect_b32 s9, 0xd00, s9
	s_lshl_b32 s12, s7, 6
	s_lshr_b32 s13, s7, 1
	s_lshl_b32 s13, s13, 8
	s_and_b32 s15, s7, 1
	s_lshl_b32 s15, s15, 6
	s_add_i32 s13, s13, s15
	s_and_b32 s15, s5, 1
	s_cmp_eq_u32 s5, 1
	s_cselect_b32 s15, 0x80, 0
	s_cmp_eq_u32 s5, 4
	s_cselect_b32 s15, 0x80, s15
	s_add_i32 s13, s13, s15
	s_cmp_eq_u32 s9, 0xb00
	s_cselect_b32 s12, s13, s12
	s_mov_b32 s14, 0x30000
	s_cmp_eq_u32 s5, 1
	s_cselect_b32 s14, 0x30000, s14
	s_cmp_eq_u32 s5, 2
	s_cselect_b32 s14, 0xb30000, s14
	s_cmp_eq_u32 s5, 3
	s_cselect_b32 s14, 0x10b0000, s14
	s_cmp_eq_u32 s5, 4
	s_cselect_b32 s14, 0x10b0000, s14
	s_cmp_eq_u32 s5, 5
	s_cselect_b32 s14, 0x1bb0000, s14
	s_cmp_eq_u32 s5, 6
	s_cselect_b32 s14, 0x2130000, s14
	s_cmp_eq_u32 s5, 7
	s_cselect_b32 s14, 0x28f0000, s14
	s_cmp_eq_u32 s5, 6
	s_cselect_b32 s15, 1, 0
	s_cmp_ge_u32 s7, 24
	s_cselect_b32 s13, s15, 0
	s_cmp_eq_u32 s13, 1
	s_cselect_b32 s14, 0x2430000, s14
	s_cselect_b32 s13, 0x600, 0
	s_sub_i32 s12, s12, s13
	s_mul_i32 s12, s12, s10
	s_lshl_b32 s13, s8, 6
	s_add_i32 s12, s12, s13
	s_lshl_b32 s12, s12, 1
	s_add_u32 s12, s12, s14
	s_add_u32 s20, s30, s12
	s_addc_u32 s21, s31, 0
	v_mul_u32_u24_e32 v71, s10, v66
	v_add_lshl_u32 v71, v71, v67, 1
	ds_read_b32 v104, v69
	ds_read_b32 v105, v69 offset:260
	ds_read_b32 v106, v69 offset:520
	ds_read_b32 v107, v69 offset:780
	ds_read_b32 v108, v69 offset:1040
	ds_read_b32 v109, v69 offset:1300
	ds_read_b32 v110, v69 offset:1560
	ds_read_b32 v111, v69 offset:1820
	s_waitcnt lgkmcnt(0)
	v_cvt_pk_bf16_f32 v116, v104, v105
	v_cvt_pk_bf16_f32 v117, v106, v107
	v_cvt_pk_bf16_f32 v118, v108, v109
	v_cvt_pk_bf16_f32 v119, v110, v111
	global_store_dwordx4 v71, v[116:119], s[20:21]
	s_barrier
	s_add_i32 s4, s2, 0xd00
	s_mov_b32 s5, 0
	s_cmp_ge_u32 s4, 0x2c0
	s_addc_u32 s5, s5, 0
	s_cmp_ge_u32 s4, 0x580
	s_addc_u32 s5, s5, 0
	s_cmp_ge_u32 s4, 0x840
	s_addc_u32 s5, s5, 0
	s_cmp_ge_u32 s4, 0xb00
	s_addc_u32 s5, s5, 0
	s_cmp_ge_u32 s4, 0xdc0
	s_addc_u32 s5, s5, 0
	s_cmp_ge_u32 s4, 0x1080
	s_addc_u32 s5, s5, 0
	s_cmp_ge_u32 s4, 0x13c0
	s_addc_u32 s5, s5, 0
	s_mul_i32 s12, s5, 0x2c0
	s_cmp_eq_u32 s5, 7
	s_cselect_b32 s13, 0x80, 0
	s_add_i32 s12, s12, s13
	s_sub_i32 s6, s4, s12
	s_cmp_eq_u32 s5, 2
	s_cselect_b32 s14, 1, 0
	s_cmp_eq_u32 s5, 5
	s_cselect_b32 s14, 1, s14
	s_mul_i32 s12, s6, 0x5d2
	s_lshr_b32 s12, s12, 16
	s_mul_i32 s15, s12, 44
	s_sub_i32 s15, s6, s15
	s_lshr_b32 s13, s6, 4
	s_and_b32 s8, s6, 15
	s_cmp_eq_u32 s14, 1
	s_cselect_b32 s7, s12, s13
	s_cselect_b32 s8, s15, s8
	s_movk_i32 s10, 0x400
	s_cselect_b32 s10, 0xb00, s10
	s_movk_i32 s9, 0xb00
	s_cselect_b32 s9, 0x400, s9
	s_cmp_eq_u32 s5, 7
	s_cselect_b32 s9, 0x400, s9
	s_cmp_eq_u32 s5, 6
	s_cselect_b32 s9, 0xd00, s9
	s_lshl_b32 s12, s5, 3
	s_lshr_b64 s[12:13], s[22:23], s12
	s_and_b32 s12, s12, 0xff
	s_add_i32 s13, s12, 1
	v_readlane_b32 s16, v241, s12
	v_readlane_b32 s17, v241, s13
	v_mul_u32_u24_e32 v70, s9, v65
	s_mul_i32 s14, s8, s9
	s_add_i32 s14, s14, s7
	s_lshl_b32 s14, s14, 8
	v_add_lshl_u32 v70, v70, v64, 2
	s_add_u32 s18, s16, s14
	s_addc_u32 s19, s17, 0
	s_lshl_b32 s15, s9, 5
	global_load_dword v80, v70, s[18:19]
	s_add_u32 s18, s18, s15
	s_addc_u32 s19, s19, 0
	global_load_dword v81, v70, s[18:19]
	s_add_u32 s18, s18, s15
	s_addc_u32 s19, s19, 0
	global_load_dword v82, v70, s[18:19]
	s_add_u32 s18, s18, s15
	s_addc_u32 s19, s19, 0
	global_load_dword v83, v70, s[18:19]
	s_add_u32 s18, s18, s15
	s_addc_u32 s19, s19, 0
	global_load_dword v84, v70, s[18:19]
	s_add_u32 s18, s18, s15
	s_addc_u32 s19, s19, 0
	global_load_dword v85, v70, s[18:19]
	s_add_u32 s18, s18, s15
	s_addc_u32 s19, s19, 0
	global_load_dword v86, v70, s[18:19]
	s_add_u32 s18, s18, s15
	s_addc_u32 s19, s19, 0
	global_load_dword v87, v70, s[18:19]
	s_waitcnt vmcnt(27)
	ds_write_b32 v68, v88
	ds_write_b32 v68, v89 offset:2080
	ds_write_b32 v68, v90 offset:4160
	ds_write_b32 v68, v91 offset:6240
	ds_write_b32 v68, v92 offset:8320
	ds_write_b32 v68, v93 offset:10400
	ds_write_b32 v68, v94 offset:12480
	ds_write_b32 v68, v95 offset:14560
	s_waitcnt lgkmcnt(0)
	s_barrier
	s_add_i32 s4, s2, 0xa00
	s_mov_b32 s5, 0
	s_cmp_ge_u32 s4, 0x2c0
	s_addc_u32 s5, s5, 0
	s_cmp_ge_u32 s4, 0x580
	s_addc_u32 s5, s5, 0
	s_cmp_ge_u32 s4, 0x840
	s_addc_u32 s5, s5, 0
	s_cmp_ge_u32 s4, 0xb00
	s_addc_u32 s5, s5, 0
	s_cmp_ge_u32 s4, 0xdc0
	s_addc_u32 s5, s5, 0
	s_cmp_ge_u32 s4, 0x1080
	s_addc_u32 s5, s5, 0
	s_cmp_ge_u32 s4, 0x13c0
	s_addc_u32 s5, s5, 0
	s_mul_i32 s12, s5, 0x2c0
	s_cmp_eq_u32 s5, 7
	s_cselect_b32 s13, 0x80, 0
	s_add_i32 s12, s12, s13
	s_sub_i32 s6, s4, s12
	s_cmp_eq_u32 s5, 2
	s_cselect_b32 s14, 1, 0
	s_cmp_eq_u32 s5, 5
	s_cselect_b32 s14, 1, s14
	s_mul_i32 s12, s6, 0x5d2
	s_lshr_b32 s12, s12, 16
	s_mul_i32 s15, s12, 44
	s_sub_i32 s15, s6, s15
	s_lshr_b32 s13, s6, 4
	s_and_b32 s8, s6, 15
	s_cmp_eq_u32 s14, 1
	s_cselect_b32 s7, s12, s13
	s_cselect_b32 s8, s15, s8
	s_movk_i32 s10, 0x400
	s_cselect_b32 s10, 0xb00, s10
	s_movk_i32 s9, 0xb00
	s_cselect_b32 s9, 0x400, s9
	s_cmp_eq_u32 s5, 7
	s_cselect_b32 s9, 0x400, s9
	s_cmp_eq_u32 s5, 6
	s_cselect_b32 s9, 0xd00, s9
	s_lshl_b32 s12, s7, 6
	s_lshr_b32 s13, s7, 1
	s_lshl_b32 s13, s13, 8
	s_and_b32 s15, s7, 1
	s_lshl_b32 s15, s15, 6
	s_add_i32 s13, s13, s15
	s_and_b32 s15, s5, 1
	s_cmp_eq_u32 s5, 1
	s_cselect_b32 s15, 0x80, 0
	s_cmp_eq_u32 s5, 4
	s_cselect_b32 s15, 0x80, s15
	s_add_i32 s13, s13, s15
	s_cmp_eq_u32 s9, 0xb00
	s_cselect_b32 s12, s13, s12
	s_mov_b32 s14, 0x30000
	s_cmp_eq_u32 s5, 1
	s_cselect_b32 s14, 0x30000, s14
	s_cmp_eq_u32 s5, 2
	s_cselect_b32 s14, 0xb30000, s14
	s_cmp_eq_u32 s5, 3
	s_cselect_b32 s14, 0x10b0000, s14
	s_cmp_eq_u32 s5, 4
	s_cselect_b32 s14, 0x10b0000, s14
	s_cmp_eq_u32 s5, 5
	s_cselect_b32 s14, 0x1bb0000, s14
	s_cmp_eq_u32 s5, 6
	s_cselect_b32 s14, 0x2130000, s14
	s_cmp_eq_u32 s5, 7
	s_cselect_b32 s14, 0x28f0000, s14
	s_cmp_eq_u32 s5, 6
	s_cselect_b32 s15, 1, 0
	s_cmp_ge_u32 s7, 24
	s_cselect_b32 s13, s15, 0
	s_cmp_eq_u32 s13, 1
	s_cselect_b32 s14, 0x2430000, s14
	s_cselect_b32 s13, 0x600, 0
	s_sub_i32 s12, s12, s13
	s_mul_i32 s12, s12, s10
	s_lshl_b32 s13, s8, 6
	s_add_i32 s12, s12, s13
	s_lshl_b32 s12, s12, 1
	s_add_u32 s12, s12, s14
	s_add_u32 s20, s30, s12
	s_addc_u32 s21, s31, 0
	v_mul_u32_u24_e32 v71, s10, v66
	v_add_lshl_u32 v71, v71, v67, 1
	ds_read_b32 v104, v69
	ds_read_b32 v105, v69 offset:260
	ds_read_b32 v106, v69 offset:520
	ds_read_b32 v107, v69 offset:780
	ds_read_b32 v108, v69 offset:1040
	ds_read_b32 v109, v69 offset:1300
	ds_read_b32 v110, v69 offset:1560
	ds_read_b32 v111, v69 offset:1820
	s_waitcnt lgkmcnt(0)
	v_cvt_pk_bf16_f32 v112, v104, v105
	v_cvt_pk_bf16_f32 v113, v106, v107
	v_cvt_pk_bf16_f32 v114, v108, v109
	v_cvt_pk_bf16_f32 v115, v110, v111
	global_store_dwordx4 v71, v[112:115], s[20:21]
	s_barrier
	s_add_i32 s4, s2, 0xe00
	s_mov_b32 s5, 0
	s_cmp_ge_u32 s4, 0x2c0
	s_addc_u32 s5, s5, 0
	s_cmp_ge_u32 s4, 0x580
	s_addc_u32 s5, s5, 0
	s_cmp_ge_u32 s4, 0x840
	s_addc_u32 s5, s5, 0
	s_cmp_ge_u32 s4, 0xb00
	s_addc_u32 s5, s5, 0
	s_cmp_ge_u32 s4, 0xdc0
	s_addc_u32 s5, s5, 0
	s_cmp_ge_u32 s4, 0x1080
	s_addc_u32 s5, s5, 0
	s_cmp_ge_u32 s4, 0x13c0
	s_addc_u32 s5, s5, 0
	s_mul_i32 s12, s5, 0x2c0
	s_cmp_eq_u32 s5, 7
	s_cselect_b32 s13, 0x80, 0
	s_add_i32 s12, s12, s13
	s_sub_i32 s6, s4, s12
	s_cmp_eq_u32 s5, 2
	s_cselect_b32 s14, 1, 0
	s_cmp_eq_u32 s5, 5
	s_cselect_b32 s14, 1, s14
	s_mul_i32 s12, s6, 0x5d2
	s_lshr_b32 s12, s12, 16
	s_mul_i32 s15, s12, 44
	s_sub_i32 s15, s6, s15
	s_lshr_b32 s13, s6, 4
	s_and_b32 s8, s6, 15
	s_cmp_eq_u32 s14, 1
	s_cselect_b32 s7, s12, s13
	s_cselect_b32 s8, s15, s8
	s_movk_i32 s10, 0x400
	s_cselect_b32 s10, 0xb00, s10
	s_movk_i32 s9, 0xb00
	s_cselect_b32 s9, 0x400, s9
	s_cmp_eq_u32 s5, 7
	s_cselect_b32 s9, 0x400, s9
	s_cmp_eq_u32 s5, 6
	s_cselect_b32 s9, 0xd00, s9
	s_lshl_b32 s12, s5, 3
	s_lshr_b64 s[12:13], s[22:23], s12
	s_and_b32 s12, s12, 0xff
	s_add_i32 s13, s12, 1
	v_readlane_b32 s16, v241, s12
	v_readlane_b32 s17, v241, s13
	v_mul_u32_u24_e32 v70, s9, v65
	s_mul_i32 s14, s8, s9
	s_add_i32 s14, s14, s7
	s_lshl_b32 s14, s14, 8
	v_add_lshl_u32 v70, v70, v64, 2
	s_add_u32 s18, s16, s14
	s_addc_u32 s19, s17, 0
	s_lshl_b32 s15, s9, 5
	global_load_dword v88, v70, s[18:19]
	s_add_u32 s18, s18, s15
	s_addc_u32 s19, s19, 0
	global_load_dword v89, v70, s[18:19]
	s_add_u32 s18, s18, s15
	s_addc_u32 s19, s19, 0
	global_load_dword v90, v70, s[18:19]
	s_add_u32 s18, s18, s15
	s_addc_u32 s19, s19, 0
	global_load_dword v91, v70, s[18:19]
	s_add_u32 s18, s18, s15
	s_addc_u32 s19, s19, 0
	global_load_dword v92, v70, s[18:19]
	s_add_u32 s18, s18, s15
	s_addc_u32 s19, s19, 0
	global_load_dword v93, v70, s[18:19]
	s_add_u32 s18, s18, s15
	s_addc_u32 s19, s19, 0
	global_load_dword v94, v70, s[18:19]
	s_add_u32 s18, s18, s15
	s_addc_u32 s19, s19, 0
	global_load_dword v95, v70, s[18:19]
	s_waitcnt vmcnt(27)
	ds_write_b32 v68, v96
	ds_write_b32 v68, v97 offset:2080
	ds_write_b32 v68, v98 offset:4160
	ds_write_b32 v68, v99 offset:6240
	ds_write_b32 v68, v100 offset:8320
	ds_write_b32 v68, v101 offset:10400
	ds_write_b32 v68, v102 offset:12480
	ds_write_b32 v68, v103 offset:14560
	s_waitcnt lgkmcnt(0)
	s_barrier
	s_add_i32 s4, s2, 0xb00
	s_mov_b32 s5, 0
	s_cmp_ge_u32 s4, 0x2c0
	s_addc_u32 s5, s5, 0
	s_cmp_ge_u32 s4, 0x580
	s_addc_u32 s5, s5, 0
	s_cmp_ge_u32 s4, 0x840
	s_addc_u32 s5, s5, 0
	s_cmp_ge_u32 s4, 0xb00
	s_addc_u32 s5, s5, 0
	s_cmp_ge_u32 s4, 0xdc0
	s_addc_u32 s5, s5, 0
	s_cmp_ge_u32 s4, 0x1080
	s_addc_u32 s5, s5, 0
	s_cmp_ge_u32 s4, 0x13c0
	s_addc_u32 s5, s5, 0
	s_mul_i32 s12, s5, 0x2c0
	s_cmp_eq_u32 s5, 7
	s_cselect_b32 s13, 0x80, 0
	s_add_i32 s12, s12, s13
	s_sub_i32 s6, s4, s12
	s_cmp_eq_u32 s5, 2
	s_cselect_b32 s14, 1, 0
	s_cmp_eq_u32 s5, 5
	s_cselect_b32 s14, 1, s14
	s_mul_i32 s12, s6, 0x5d2
	s_lshr_b32 s12, s12, 16
	s_mul_i32 s15, s12, 44
	s_sub_i32 s15, s6, s15
	s_lshr_b32 s13, s6, 4
	s_and_b32 s8, s6, 15
	s_cmp_eq_u32 s14, 1
	s_cselect_b32 s7, s12, s13
	s_cselect_b32 s8, s15, s8
	s_movk_i32 s10, 0x400
	s_cselect_b32 s10, 0xb00, s10
	s_movk_i32 s9, 0xb00
	s_cselect_b32 s9, 0x400, s9
	s_cmp_eq_u32 s5, 7
	s_cselect_b32 s9, 0x400, s9
	s_cmp_eq_u32 s5, 6
	s_cselect_b32 s9, 0xd00, s9
	s_lshl_b32 s12, s7, 6
	s_lshr_b32 s13, s7, 1
	s_lshl_b32 s13, s13, 8
	s_and_b32 s15, s7, 1
	s_lshl_b32 s15, s15, 6
	s_add_i32 s13, s13, s15
	s_and_b32 s15, s5, 1
	s_cmp_eq_u32 s5, 1
	s_cselect_b32 s15, 0x80, 0
	s_cmp_eq_u32 s5, 4
	s_cselect_b32 s15, 0x80, s15
	s_add_i32 s13, s13, s15
	s_cmp_eq_u32 s9, 0xb00
	s_cselect_b32 s12, s13, s12
	s_mov_b32 s14, 0x30000
	s_cmp_eq_u32 s5, 1
	s_cselect_b32 s14, 0x30000, s14
	s_cmp_eq_u32 s5, 2
	s_cselect_b32 s14, 0xb30000, s14
	s_cmp_eq_u32 s5, 3
	s_cselect_b32 s14, 0x10b0000, s14
	s_cmp_eq_u32 s5, 4
	s_cselect_b32 s14, 0x10b0000, s14
	s_cmp_eq_u32 s5, 5
	s_cselect_b32 s14, 0x1bb0000, s14
	s_cmp_eq_u32 s5, 6
	s_cselect_b32 s14, 0x2130000, s14
	s_cmp_eq_u32 s5, 7
	s_cselect_b32 s14, 0x28f0000, s14
	s_cmp_eq_u32 s5, 6
	s_cselect_b32 s15, 1, 0
	s_cmp_ge_u32 s7, 24
	s_cselect_b32 s13, s15, 0
	s_cmp_eq_u32 s13, 1
	s_cselect_b32 s14, 0x2430000, s14
	s_cselect_b32 s13, 0x600, 0
	s_sub_i32 s12, s12, s13
	s_mul_i32 s12, s12, s10
	s_lshl_b32 s13, s8, 6
	s_add_i32 s12, s12, s13
	s_lshl_b32 s12, s12, 1
	s_add_u32 s12, s12, s14
	s_add_u32 s20, s30, s12
	s_addc_u32 s21, s31, 0
	v_mul_u32_u24_e32 v71, s10, v66
	v_add_lshl_u32 v71, v71, v67, 1
	ds_read_b32 v104, v69
	ds_read_b32 v105, v69 offset:260
	ds_read_b32 v106, v69 offset:520
	ds_read_b32 v107, v69 offset:780
	ds_read_b32 v108, v69 offset:1040
	ds_read_b32 v109, v69 offset:1300
	ds_read_b32 v110, v69 offset:1560
	ds_read_b32 v111, v69 offset:1820
	s_waitcnt lgkmcnt(0)
	v_cvt_pk_bf16_f32 v116, v104, v105
	v_cvt_pk_bf16_f32 v117, v106, v107
	v_cvt_pk_bf16_f32 v118, v108, v109
	v_cvt_pk_bf16_f32 v119, v110, v111
	global_store_dwordx4 v71, v[116:119], s[20:21]
	s_barrier
	s_add_i32 s4, s2, 0xf00
	s_mov_b32 s5, 0
	s_cmp_ge_u32 s4, 0x2c0
	s_addc_u32 s5, s5, 0
	s_cmp_ge_u32 s4, 0x580
	s_addc_u32 s5, s5, 0
	s_cmp_ge_u32 s4, 0x840
	s_addc_u32 s5, s5, 0
	s_cmp_ge_u32 s4, 0xb00
	s_addc_u32 s5, s5, 0
	s_cmp_ge_u32 s4, 0xdc0
	s_addc_u32 s5, s5, 0
	s_cmp_ge_u32 s4, 0x1080
	s_addc_u32 s5, s5, 0
	s_cmp_ge_u32 s4, 0x13c0
	s_addc_u32 s5, s5, 0
	s_mul_i32 s12, s5, 0x2c0
	s_cmp_eq_u32 s5, 7
	s_cselect_b32 s13, 0x80, 0
	s_add_i32 s12, s12, s13
	s_sub_i32 s6, s4, s12
	s_cmp_eq_u32 s5, 2
	s_cselect_b32 s14, 1, 0
	s_cmp_eq_u32 s5, 5
	s_cselect_b32 s14, 1, s14
	s_mul_i32 s12, s6, 0x5d2
	s_lshr_b32 s12, s12, 16
	s_mul_i32 s15, s12, 44
	s_sub_i32 s15, s6, s15
	s_lshr_b32 s13, s6, 4
	s_and_b32 s8, s6, 15
	s_cmp_eq_u32 s14, 1
	s_cselect_b32 s7, s12, s13
	s_cselect_b32 s8, s15, s8
	s_movk_i32 s10, 0x400
	s_cselect_b32 s10, 0xb00, s10
	s_movk_i32 s9, 0xb00
	s_cselect_b32 s9, 0x400, s9
	s_cmp_eq_u32 s5, 7
	s_cselect_b32 s9, 0x400, s9
	s_cmp_eq_u32 s5, 6
	s_cselect_b32 s9, 0xd00, s9
	s_lshl_b32 s12, s5, 3
	s_lshr_b64 s[12:13], s[22:23], s12
	s_and_b32 s12, s12, 0xff
	s_add_i32 s13, s12, 1
	v_readlane_b32 s16, v241, s12
	v_readlane_b32 s17, v241, s13
	v_mul_u32_u24_e32 v70, s9, v65
	s_mul_i32 s14, s8, s9
	s_add_i32 s14, s14, s7
	s_lshl_b32 s14, s14, 8
	v_add_lshl_u32 v70, v70, v64, 2
	s_add_u32 s18, s16, s14
	s_addc_u32 s19, s17, 0
	s_lshl_b32 s15, s9, 5
	global_load_dword v96, v70, s[18:19]
	s_add_u32 s18, s18, s15
	s_addc_u32 s19, s19, 0
	global_load_dword v97, v70, s[18:19]
	s_add_u32 s18, s18, s15
	s_addc_u32 s19, s19, 0
	global_load_dword v98, v70, s[18:19]
	s_add_u32 s18, s18, s15
	s_addc_u32 s19, s19, 0
	global_load_dword v99, v70, s[18:19]
	s_add_u32 s18, s18, s15
	s_addc_u32 s19, s19, 0
	global_load_dword v100, v70, s[18:19]
	s_add_u32 s18, s18, s15
	s_addc_u32 s19, s19, 0
	global_load_dword v101, v70, s[18:19]
	s_add_u32 s18, s18, s15
	s_addc_u32 s19, s19, 0
	global_load_dword v102, v70, s[18:19]
	s_add_u32 s18, s18, s15
	s_addc_u32 s19, s19, 0
	global_load_dword v103, v70, s[18:19]
	s_waitcnt vmcnt(27)
	ds_write_b32 v68, v72
	ds_write_b32 v68, v73 offset:2080
	ds_write_b32 v68, v74 offset:4160
	ds_write_b32 v68, v75 offset:6240
	ds_write_b32 v68, v76 offset:8320
	ds_write_b32 v68, v77 offset:10400
	ds_write_b32 v68, v78 offset:12480
	ds_write_b32 v68, v79 offset:14560
	s_waitcnt lgkmcnt(0)
	s_barrier
	s_add_i32 s4, s2, 0xc00
	s_mov_b32 s5, 0
	s_cmp_ge_u32 s4, 0x2c0
	s_addc_u32 s5, s5, 0
	s_cmp_ge_u32 s4, 0x580
	s_addc_u32 s5, s5, 0
	s_cmp_ge_u32 s4, 0x840
	s_addc_u32 s5, s5, 0
	s_cmp_ge_u32 s4, 0xb00
	s_addc_u32 s5, s5, 0
	s_cmp_ge_u32 s4, 0xdc0
	s_addc_u32 s5, s5, 0
	s_cmp_ge_u32 s4, 0x1080
	s_addc_u32 s5, s5, 0
	s_cmp_ge_u32 s4, 0x13c0
	s_addc_u32 s5, s5, 0
	s_mul_i32 s12, s5, 0x2c0
	s_cmp_eq_u32 s5, 7
	s_cselect_b32 s13, 0x80, 0
	s_add_i32 s12, s12, s13
	s_sub_i32 s6, s4, s12
	s_cmp_eq_u32 s5, 2
	s_cselect_b32 s14, 1, 0
	s_cmp_eq_u32 s5, 5
	s_cselect_b32 s14, 1, s14
	s_mul_i32 s12, s6, 0x5d2
	s_lshr_b32 s12, s12, 16
	s_mul_i32 s15, s12, 44
	s_sub_i32 s15, s6, s15
	s_lshr_b32 s13, s6, 4
	s_and_b32 s8, s6, 15
	s_cmp_eq_u32 s14, 1
	s_cselect_b32 s7, s12, s13
	s_cselect_b32 s8, s15, s8
	s_movk_i32 s10, 0x400
	s_cselect_b32 s10, 0xb00, s10
	s_movk_i32 s9, 0xb00
	s_cselect_b32 s9, 0x400, s9
	s_cmp_eq_u32 s5, 7
	s_cselect_b32 s9, 0x400, s9
	s_cmp_eq_u32 s5, 6
	s_cselect_b32 s9, 0xd00, s9
	s_lshl_b32 s12, s7, 6
	s_lshr_b32 s13, s7, 1
	s_lshl_b32 s13, s13, 8
	s_and_b32 s15, s7, 1
	s_lshl_b32 s15, s15, 6
	s_add_i32 s13, s13, s15
	s_and_b32 s15, s5, 1
	s_cmp_eq_u32 s5, 1
	s_cselect_b32 s15, 0x80, 0
	s_cmp_eq_u32 s5, 4
	s_cselect_b32 s15, 0x80, s15
	s_add_i32 s13, s13, s15
	s_cmp_eq_u32 s9, 0xb00
	s_cselect_b32 s12, s13, s12
	s_mov_b32 s14, 0x30000
	s_cmp_eq_u32 s5, 1
	s_cselect_b32 s14, 0x30000, s14
	s_cmp_eq_u32 s5, 2
	s_cselect_b32 s14, 0xb30000, s14
	s_cmp_eq_u32 s5, 3
	s_cselect_b32 s14, 0x10b0000, s14
	s_cmp_eq_u32 s5, 4
	s_cselect_b32 s14, 0x10b0000, s14
	s_cmp_eq_u32 s5, 5
	s_cselect_b32 s14, 0x1bb0000, s14
	s_cmp_eq_u32 s5, 6
	s_cselect_b32 s14, 0x2130000, s14
	s_cmp_eq_u32 s5, 7
	s_cselect_b32 s14, 0x28f0000, s14
	s_cmp_eq_u32 s5, 6
	s_cselect_b32 s15, 1, 0
	s_cmp_ge_u32 s7, 24
	s_cselect_b32 s13, s15, 0
	s_cmp_eq_u32 s13, 1
	s_cselect_b32 s14, 0x2430000, s14
	s_cselect_b32 s13, 0x600, 0
	s_sub_i32 s12, s12, s13
	s_mul_i32 s12, s12, s10
	s_lshl_b32 s13, s8, 6
	s_add_i32 s12, s12, s13
	s_lshl_b32 s12, s12, 1
	s_add_u32 s12, s12, s14
	s_add_u32 s20, s30, s12
	s_addc_u32 s21, s31, 0
	v_mul_u32_u24_e32 v71, s10, v66
	v_add_lshl_u32 v71, v71, v67, 1
	ds_read_b32 v104, v69
	ds_read_b32 v105, v69 offset:260
	ds_read_b32 v106, v69 offset:520
	ds_read_b32 v107, v69 offset:780
	ds_read_b32 v108, v69 offset:1040
	ds_read_b32 v109, v69 offset:1300
	ds_read_b32 v110, v69 offset:1560
	ds_read_b32 v111, v69 offset:1820
	s_waitcnt lgkmcnt(0)
	v_cvt_pk_bf16_f32 v112, v104, v105
	v_cvt_pk_bf16_f32 v113, v106, v107
	v_cvt_pk_bf16_f32 v114, v108, v109
	v_cvt_pk_bf16_f32 v115, v110, v111
	global_store_dwordx4 v71, v[112:115], s[20:21]
	s_barrier
	s_add_i32 s4, s2, 0x1000
	s_mov_b32 s5, 0
	s_cmp_ge_u32 s4, 0x2c0
	s_addc_u32 s5, s5, 0
	s_cmp_ge_u32 s4, 0x580
	s_addc_u32 s5, s5, 0
	s_cmp_ge_u32 s4, 0x840
	s_addc_u32 s5, s5, 0
	s_cmp_ge_u32 s4, 0xb00
	s_addc_u32 s5, s5, 0
	s_cmp_ge_u32 s4, 0xdc0
	s_addc_u32 s5, s5, 0
	s_cmp_ge_u32 s4, 0x1080
	s_addc_u32 s5, s5, 0
	s_cmp_ge_u32 s4, 0x13c0
	s_addc_u32 s5, s5, 0
	s_mul_i32 s12, s5, 0x2c0
	s_cmp_eq_u32 s5, 7
	s_cselect_b32 s13, 0x80, 0
	s_add_i32 s12, s12, s13
	s_sub_i32 s6, s4, s12
	s_cmp_eq_u32 s5, 2
	s_cselect_b32 s14, 1, 0
	s_cmp_eq_u32 s5, 5
	s_cselect_b32 s14, 1, s14
	s_mul_i32 s12, s6, 0x5d2
	s_lshr_b32 s12, s12, 16
	s_mul_i32 s15, s12, 44
	s_sub_i32 s15, s6, s15
	s_lshr_b32 s13, s6, 4
	s_and_b32 s8, s6, 15
	s_cmp_eq_u32 s14, 1
	s_cselect_b32 s7, s12, s13
	s_cselect_b32 s8, s15, s8
	s_movk_i32 s10, 0x400
	s_cselect_b32 s10, 0xb00, s10
	s_movk_i32 s9, 0xb00
	s_cselect_b32 s9, 0x400, s9
	s_cmp_eq_u32 s5, 7
	s_cselect_b32 s9, 0x400, s9
	s_cmp_eq_u32 s5, 6
	s_cselect_b32 s9, 0xd00, s9
	s_lshl_b32 s12, s5, 3
	s_lshr_b64 s[12:13], s[22:23], s12
	s_and_b32 s12, s12, 0xff
	s_add_i32 s13, s12, 1
	v_readlane_b32 s16, v241, s12
	v_readlane_b32 s17, v241, s13
	v_mul_u32_u24_e32 v70, s9, v65
	s_mul_i32 s14, s8, s9
	s_add_i32 s14, s14, s7
	s_lshl_b32 s14, s14, 8
	v_add_lshl_u32 v70, v70, v64, 2
	s_add_u32 s18, s16, s14
	s_addc_u32 s19, s17, 0
	s_lshl_b32 s15, s9, 5
	global_load_dword v72, v70, s[18:19]
	s_add_u32 s18, s18, s15
	s_addc_u32 s19, s19, 0
	global_load_dword v73, v70, s[18:19]
	s_add_u32 s18, s18, s15
	s_addc_u32 s19, s19, 0
	global_load_dword v74, v70, s[18:19]
	s_add_u32 s18, s18, s15
	s_addc_u32 s19, s19, 0
	global_load_dword v75, v70, s[18:19]
	s_add_u32 s18, s18, s15
	s_addc_u32 s19, s19, 0
	global_load_dword v76, v70, s[18:19]
	s_add_u32 s18, s18, s15
	s_addc_u32 s19, s19, 0
	global_load_dword v77, v70, s[18:19]
	s_add_u32 s18, s18, s15
	s_addc_u32 s19, s19, 0
	global_load_dword v78, v70, s[18:19]
	s_add_u32 s18, s18, s15
	s_addc_u32 s19, s19, 0
	global_load_dword v79, v70, s[18:19]
	s_waitcnt vmcnt(27)
	ds_write_b32 v68, v80
	ds_write_b32 v68, v81 offset:2080
	ds_write_b32 v68, v82 offset:4160
	ds_write_b32 v68, v83 offset:6240
	ds_write_b32 v68, v84 offset:8320
	ds_write_b32 v68, v85 offset:10400
	ds_write_b32 v68, v86 offset:12480
	ds_write_b32 v68, v87 offset:14560
	s_waitcnt lgkmcnt(0)
	s_barrier
	s_add_i32 s4, s2, 0xd00
	s_mov_b32 s5, 0
	s_cmp_ge_u32 s4, 0x2c0
	s_addc_u32 s5, s5, 0
	s_cmp_ge_u32 s4, 0x580
	s_addc_u32 s5, s5, 0
	s_cmp_ge_u32 s4, 0x840
	s_addc_u32 s5, s5, 0
	s_cmp_ge_u32 s4, 0xb00
	s_addc_u32 s5, s5, 0
	s_cmp_ge_u32 s4, 0xdc0
	s_addc_u32 s5, s5, 0
	s_cmp_ge_u32 s4, 0x1080
	s_addc_u32 s5, s5, 0
	s_cmp_ge_u32 s4, 0x13c0
	s_addc_u32 s5, s5, 0
	s_mul_i32 s12, s5, 0x2c0
	s_cmp_eq_u32 s5, 7
	s_cselect_b32 s13, 0x80, 0
	s_add_i32 s12, s12, s13
	s_sub_i32 s6, s4, s12
	s_cmp_eq_u32 s5, 2
	s_cselect_b32 s14, 1, 0
	s_cmp_eq_u32 s5, 5
	s_cselect_b32 s14, 1, s14
	s_mul_i32 s12, s6, 0x5d2
	s_lshr_b32 s12, s12, 16
	s_mul_i32 s15, s12, 44
	s_sub_i32 s15, s6, s15
	s_lshr_b32 s13, s6, 4
	s_and_b32 s8, s6, 15
	s_cmp_eq_u32 s14, 1
	s_cselect_b32 s7, s12, s13
	s_cselect_b32 s8, s15, s8
	s_movk_i32 s10, 0x400
	s_cselect_b32 s10, 0xb00, s10
	s_movk_i32 s9, 0xb00
	s_cselect_b32 s9, 0x400, s9
	s_cmp_eq_u32 s5, 7
	s_cselect_b32 s9, 0x400, s9
	s_cmp_eq_u32 s5, 6
	s_cselect_b32 s9, 0xd00, s9
	s_lshl_b32 s12, s7, 6
	s_lshr_b32 s13, s7, 1
	s_lshl_b32 s13, s13, 8
	s_and_b32 s15, s7, 1
	s_lshl_b32 s15, s15, 6
	s_add_i32 s13, s13, s15
	s_and_b32 s15, s5, 1
	s_cmp_eq_u32 s5, 1
	s_cselect_b32 s15, 0x80, 0
	s_cmp_eq_u32 s5, 4
	s_cselect_b32 s15, 0x80, s15
	s_add_i32 s13, s13, s15
	s_cmp_eq_u32 s9, 0xb00
	s_cselect_b32 s12, s13, s12
	s_mov_b32 s14, 0x30000
	s_cmp_eq_u32 s5, 1
	s_cselect_b32 s14, 0x30000, s14
	s_cmp_eq_u32 s5, 2
	s_cselect_b32 s14, 0xb30000, s14
	s_cmp_eq_u32 s5, 3
	s_cselect_b32 s14, 0x10b0000, s14
	s_cmp_eq_u32 s5, 4
	s_cselect_b32 s14, 0x10b0000, s14
	s_cmp_eq_u32 s5, 5
	s_cselect_b32 s14, 0x1bb0000, s14
	s_cmp_eq_u32 s5, 6
	s_cselect_b32 s14, 0x2130000, s14
	s_cmp_eq_u32 s5, 7
	s_cselect_b32 s14, 0x28f0000, s14
	s_cmp_eq_u32 s5, 6
	s_cselect_b32 s15, 1, 0
	s_cmp_ge_u32 s7, 24
	s_cselect_b32 s13, s15, 0
	s_cmp_eq_u32 s13, 1
	s_cselect_b32 s14, 0x2430000, s14
	s_cselect_b32 s13, 0x600, 0
	s_sub_i32 s12, s12, s13
	s_mul_i32 s12, s12, s10
	s_lshl_b32 s13, s8, 6
	s_add_i32 s12, s12, s13
	s_lshl_b32 s12, s12, 1
	s_add_u32 s12, s12, s14
	s_add_u32 s20, s30, s12
	s_addc_u32 s21, s31, 0
	v_mul_u32_u24_e32 v71, s10, v66
	v_add_lshl_u32 v71, v71, v67, 1
	ds_read_b32 v104, v69
	ds_read_b32 v105, v69 offset:260
	ds_read_b32 v106, v69 offset:520
	ds_read_b32 v107, v69 offset:780
	ds_read_b32 v108, v69 offset:1040
	ds_read_b32 v109, v69 offset:1300
	ds_read_b32 v110, v69 offset:1560
	ds_read_b32 v111, v69 offset:1820
	s_waitcnt lgkmcnt(0)
	v_cvt_pk_bf16_f32 v116, v104, v105
	v_cvt_pk_bf16_f32 v117, v106, v107
	v_cvt_pk_bf16_f32 v118, v108, v109
	v_cvt_pk_bf16_f32 v119, v110, v111
	global_store_dwordx4 v71, v[116:119], s[20:21]
	s_barrier
	s_add_i32 s4, s2, 0x1100
	s_mov_b32 s5, 0
	s_cmp_ge_u32 s4, 0x2c0
	s_addc_u32 s5, s5, 0
	s_cmp_ge_u32 s4, 0x580
	s_addc_u32 s5, s5, 0
	s_cmp_ge_u32 s4, 0x840
	s_addc_u32 s5, s5, 0
	s_cmp_ge_u32 s4, 0xb00
	s_addc_u32 s5, s5, 0
	s_cmp_ge_u32 s4, 0xdc0
	s_addc_u32 s5, s5, 0
	s_cmp_ge_u32 s4, 0x1080
	s_addc_u32 s5, s5, 0
	s_cmp_ge_u32 s4, 0x13c0
	s_addc_u32 s5, s5, 0
	s_mul_i32 s12, s5, 0x2c0
	s_cmp_eq_u32 s5, 7
	s_cselect_b32 s13, 0x80, 0
	s_add_i32 s12, s12, s13
	s_sub_i32 s6, s4, s12
	s_cmp_eq_u32 s5, 2
	s_cselect_b32 s14, 1, 0
	s_cmp_eq_u32 s5, 5
	s_cselect_b32 s14, 1, s14
	s_mul_i32 s12, s6, 0x5d2
	s_lshr_b32 s12, s12, 16
	s_mul_i32 s15, s12, 44
	s_sub_i32 s15, s6, s15
	s_lshr_b32 s13, s6, 4
	s_and_b32 s8, s6, 15
	s_cmp_eq_u32 s14, 1
	s_cselect_b32 s7, s12, s13
	s_cselect_b32 s8, s15, s8
	s_movk_i32 s10, 0x400
	s_cselect_b32 s10, 0xb00, s10
	s_movk_i32 s9, 0xb00
	s_cselect_b32 s9, 0x400, s9
	s_cmp_eq_u32 s5, 7
	s_cselect_b32 s9, 0x400, s9
	s_cmp_eq_u32 s5, 6
	s_cselect_b32 s9, 0xd00, s9
	s_lshl_b32 s12, s5, 3
	s_lshr_b64 s[12:13], s[22:23], s12
	s_and_b32 s12, s12, 0xff
	s_add_i32 s13, s12, 1
	v_readlane_b32 s16, v241, s12
	v_readlane_b32 s17, v241, s13
	v_mul_u32_u24_e32 v70, s9, v65
	s_mul_i32 s14, s8, s9
	s_add_i32 s14, s14, s7
	s_lshl_b32 s14, s14, 8
	v_add_lshl_u32 v70, v70, v64, 2
	s_add_u32 s18, s16, s14
	s_addc_u32 s19, s17, 0
	s_lshl_b32 s15, s9, 5
	global_load_dword v80, v70, s[18:19]
	s_add_u32 s18, s18, s15
	s_addc_u32 s19, s19, 0
	global_load_dword v81, v70, s[18:19]
	s_add_u32 s18, s18, s15
	s_addc_u32 s19, s19, 0
	global_load_dword v82, v70, s[18:19]
	s_add_u32 s18, s18, s15
	s_addc_u32 s19, s19, 0
	global_load_dword v83, v70, s[18:19]
	s_add_u32 s18, s18, s15
	s_addc_u32 s19, s19, 0
	global_load_dword v84, v70, s[18:19]
	s_add_u32 s18, s18, s15
	s_addc_u32 s19, s19, 0
	global_load_dword v85, v70, s[18:19]
	s_add_u32 s18, s18, s15
	s_addc_u32 s19, s19, 0
	global_load_dword v86, v70, s[18:19]
	s_add_u32 s18, s18, s15
	s_addc_u32 s19, s19, 0
	global_load_dword v87, v70, s[18:19]
	s_waitcnt vmcnt(27)
	ds_write_b32 v68, v88
	ds_write_b32 v68, v89 offset:2080
	ds_write_b32 v68, v90 offset:4160
	ds_write_b32 v68, v91 offset:6240
	ds_write_b32 v68, v92 offset:8320
	ds_write_b32 v68, v93 offset:10400
	ds_write_b32 v68, v94 offset:12480
	ds_write_b32 v68, v95 offset:14560
	s_waitcnt lgkmcnt(0)
	s_barrier
	s_add_i32 s4, s2, 0xe00
	s_mov_b32 s5, 0
	s_cmp_ge_u32 s4, 0x2c0
	s_addc_u32 s5, s5, 0
	s_cmp_ge_u32 s4, 0x580
	s_addc_u32 s5, s5, 0
	s_cmp_ge_u32 s4, 0x840
	s_addc_u32 s5, s5, 0
	s_cmp_ge_u32 s4, 0xb00
	s_addc_u32 s5, s5, 0
	s_cmp_ge_u32 s4, 0xdc0
	s_addc_u32 s5, s5, 0
	s_cmp_ge_u32 s4, 0x1080
	s_addc_u32 s5, s5, 0
	s_cmp_ge_u32 s4, 0x13c0
	s_addc_u32 s5, s5, 0
	s_mul_i32 s12, s5, 0x2c0
	s_cmp_eq_u32 s5, 7
	s_cselect_b32 s13, 0x80, 0
	s_add_i32 s12, s12, s13
	s_sub_i32 s6, s4, s12
	s_cmp_eq_u32 s5, 2
	s_cselect_b32 s14, 1, 0
	s_cmp_eq_u32 s5, 5
	s_cselect_b32 s14, 1, s14
	s_mul_i32 s12, s6, 0x5d2
	s_lshr_b32 s12, s12, 16
	s_mul_i32 s15, s12, 44
	s_sub_i32 s15, s6, s15
	s_lshr_b32 s13, s6, 4
	s_and_b32 s8, s6, 15
	s_cmp_eq_u32 s14, 1
	s_cselect_b32 s7, s12, s13
	s_cselect_b32 s8, s15, s8
	s_movk_i32 s10, 0x400
	s_cselect_b32 s10, 0xb00, s10
	s_movk_i32 s9, 0xb00
	s_cselect_b32 s9, 0x400, s9
	s_cmp_eq_u32 s5, 7
	s_cselect_b32 s9, 0x400, s9
	s_cmp_eq_u32 s5, 6
	s_cselect_b32 s9, 0xd00, s9
	s_lshl_b32 s12, s7, 6
	s_lshr_b32 s13, s7, 1
	s_lshl_b32 s13, s13, 8
	s_and_b32 s15, s7, 1
	s_lshl_b32 s15, s15, 6
	s_add_i32 s13, s13, s15
	s_and_b32 s15, s5, 1
	s_cmp_eq_u32 s5, 1
	s_cselect_b32 s15, 0x80, 0
	s_cmp_eq_u32 s5, 4
	s_cselect_b32 s15, 0x80, s15
	s_add_i32 s13, s13, s15
	s_cmp_eq_u32 s9, 0xb00
	s_cselect_b32 s12, s13, s12
	s_mov_b32 s14, 0x30000
	s_cmp_eq_u32 s5, 1
	s_cselect_b32 s14, 0x30000, s14
	s_cmp_eq_u32 s5, 2
	s_cselect_b32 s14, 0xb30000, s14
	s_cmp_eq_u32 s5, 3
	s_cselect_b32 s14, 0x10b0000, s14
	s_cmp_eq_u32 s5, 4
	s_cselect_b32 s14, 0x10b0000, s14
	s_cmp_eq_u32 s5, 5
	s_cselect_b32 s14, 0x1bb0000, s14
	s_cmp_eq_u32 s5, 6
	s_cselect_b32 s14, 0x2130000, s14
	s_cmp_eq_u32 s5, 7
	s_cselect_b32 s14, 0x28f0000, s14
	s_cmp_eq_u32 s5, 6
	s_cselect_b32 s15, 1, 0
	s_cmp_ge_u32 s7, 24
	s_cselect_b32 s13, s15, 0
	s_cmp_eq_u32 s13, 1
	s_cselect_b32 s14, 0x2430000, s14
	s_cselect_b32 s13, 0x600, 0
	s_sub_i32 s12, s12, s13
	s_mul_i32 s12, s12, s10
	s_lshl_b32 s13, s8, 6
	s_add_i32 s12, s12, s13
	s_lshl_b32 s12, s12, 1
	s_add_u32 s12, s12, s14
	s_add_u32 s20, s30, s12
	s_addc_u32 s21, s31, 0
	v_mul_u32_u24_e32 v71, s10, v66
	v_add_lshl_u32 v71, v71, v67, 1
	ds_read_b32 v104, v69
	ds_read_b32 v105, v69 offset:260
	ds_read_b32 v106, v69 offset:520
	ds_read_b32 v107, v69 offset:780
	ds_read_b32 v108, v69 offset:1040
	ds_read_b32 v109, v69 offset:1300
	ds_read_b32 v110, v69 offset:1560
	ds_read_b32 v111, v69 offset:1820
	s_waitcnt lgkmcnt(0)
	v_cvt_pk_bf16_f32 v112, v104, v105
	v_cvt_pk_bf16_f32 v113, v106, v107
	v_cvt_pk_bf16_f32 v114, v108, v109
	v_cvt_pk_bf16_f32 v115, v110, v111
	global_store_dwordx4 v71, v[112:115], s[20:21]
	s_barrier
	s_add_i32 s4, s2, 0x1200
	s_mov_b32 s5, 0
	s_cmp_ge_u32 s4, 0x2c0
	s_addc_u32 s5, s5, 0
	s_cmp_ge_u32 s4, 0x580
	s_addc_u32 s5, s5, 0
	s_cmp_ge_u32 s4, 0x840
	s_addc_u32 s5, s5, 0
	s_cmp_ge_u32 s4, 0xb00
	s_addc_u32 s5, s5, 0
	s_cmp_ge_u32 s4, 0xdc0
	s_addc_u32 s5, s5, 0
	s_cmp_ge_u32 s4, 0x1080
	s_addc_u32 s5, s5, 0
	s_cmp_ge_u32 s4, 0x13c0
	s_addc_u32 s5, s5, 0
	s_mul_i32 s12, s5, 0x2c0
	s_cmp_eq_u32 s5, 7
	s_cselect_b32 s13, 0x80, 0
	s_add_i32 s12, s12, s13
	s_sub_i32 s6, s4, s12
	s_cmp_eq_u32 s5, 2
	s_cselect_b32 s14, 1, 0
	s_cmp_eq_u32 s5, 5
	s_cselect_b32 s14, 1, s14
	s_mul_i32 s12, s6, 0x5d2
	s_lshr_b32 s12, s12, 16
	s_mul_i32 s15, s12, 44
	s_sub_i32 s15, s6, s15
	s_lshr_b32 s13, s6, 4
	s_and_b32 s8, s6, 15
	s_cmp_eq_u32 s14, 1
	s_cselect_b32 s7, s12, s13
	s_cselect_b32 s8, s15, s8
	s_movk_i32 s10, 0x400
	s_cselect_b32 s10, 0xb00, s10
	s_movk_i32 s9, 0xb00
	s_cselect_b32 s9, 0x400, s9
	s_cmp_eq_u32 s5, 7
	s_cselect_b32 s9, 0x400, s9
	s_cmp_eq_u32 s5, 6
	s_cselect_b32 s9, 0xd00, s9
	s_lshl_b32 s12, s5, 3
	s_lshr_b64 s[12:13], s[22:23], s12
	s_and_b32 s12, s12, 0xff
	s_add_i32 s13, s12, 1
	v_readlane_b32 s16, v241, s12
	v_readlane_b32 s17, v241, s13
	v_mul_u32_u24_e32 v70, s9, v65
	s_mul_i32 s14, s8, s9
	s_add_i32 s14, s14, s7
	s_lshl_b32 s14, s14, 8
	v_add_lshl_u32 v70, v70, v64, 2
	s_add_u32 s18, s16, s14
	s_addc_u32 s19, s17, 0
	s_lshl_b32 s15, s9, 5
	global_load_dword v88, v70, s[18:19]
	s_add_u32 s18, s18, s15
	s_addc_u32 s19, s19, 0
	global_load_dword v89, v70, s[18:19]
	s_add_u32 s18, s18, s15
	s_addc_u32 s19, s19, 0
	global_load_dword v90, v70, s[18:19]
	s_add_u32 s18, s18, s15
	s_addc_u32 s19, s19, 0
	global_load_dword v91, v70, s[18:19]
	s_add_u32 s18, s18, s15
	s_addc_u32 s19, s19, 0
	global_load_dword v92, v70, s[18:19]
	s_add_u32 s18, s18, s15
	s_addc_u32 s19, s19, 0
	global_load_dword v93, v70, s[18:19]
	s_add_u32 s18, s18, s15
	s_addc_u32 s19, s19, 0
	global_load_dword v94, v70, s[18:19]
	s_add_u32 s18, s18, s15
	s_addc_u32 s19, s19, 0
	global_load_dword v95, v70, s[18:19]
	s_waitcnt vmcnt(27)
	ds_write_b32 v68, v96
	ds_write_b32 v68, v97 offset:2080
	ds_write_b32 v68, v98 offset:4160
	ds_write_b32 v68, v99 offset:6240
	ds_write_b32 v68, v100 offset:8320
	ds_write_b32 v68, v101 offset:10400
	ds_write_b32 v68, v102 offset:12480
	ds_write_b32 v68, v103 offset:14560
	s_waitcnt lgkmcnt(0)
	s_barrier
	s_add_i32 s4, s2, 0xf00
	s_mov_b32 s5, 0
	s_cmp_ge_u32 s4, 0x2c0
	s_addc_u32 s5, s5, 0
	s_cmp_ge_u32 s4, 0x580
	s_addc_u32 s5, s5, 0
	s_cmp_ge_u32 s4, 0x840
	s_addc_u32 s5, s5, 0
	s_cmp_ge_u32 s4, 0xb00
	s_addc_u32 s5, s5, 0
	s_cmp_ge_u32 s4, 0xdc0
	s_addc_u32 s5, s5, 0
	s_cmp_ge_u32 s4, 0x1080
	s_addc_u32 s5, s5, 0
	s_cmp_ge_u32 s4, 0x13c0
	s_addc_u32 s5, s5, 0
	s_mul_i32 s12, s5, 0x2c0
	s_cmp_eq_u32 s5, 7
	s_cselect_b32 s13, 0x80, 0
	s_add_i32 s12, s12, s13
	s_sub_i32 s6, s4, s12
	s_cmp_eq_u32 s5, 2
	s_cselect_b32 s14, 1, 0
	s_cmp_eq_u32 s5, 5
	s_cselect_b32 s14, 1, s14
	s_mul_i32 s12, s6, 0x5d2
	s_lshr_b32 s12, s12, 16
	s_mul_i32 s15, s12, 44
	s_sub_i32 s15, s6, s15
	s_lshr_b32 s13, s6, 4
	s_and_b32 s8, s6, 15
	s_cmp_eq_u32 s14, 1
	s_cselect_b32 s7, s12, s13
	s_cselect_b32 s8, s15, s8
	s_movk_i32 s10, 0x400
	s_cselect_b32 s10, 0xb00, s10
	s_movk_i32 s9, 0xb00
	s_cselect_b32 s9, 0x400, s9
	s_cmp_eq_u32 s5, 7
	s_cselect_b32 s9, 0x400, s9
	s_cmp_eq_u32 s5, 6
	s_cselect_b32 s9, 0xd00, s9
	s_lshl_b32 s12, s7, 6
	s_lshr_b32 s13, s7, 1
	s_lshl_b32 s13, s13, 8
	s_and_b32 s15, s7, 1
	s_lshl_b32 s15, s15, 6
	s_add_i32 s13, s13, s15
	s_and_b32 s15, s5, 1
	s_cmp_eq_u32 s5, 1
	s_cselect_b32 s15, 0x80, 0
	s_cmp_eq_u32 s5, 4
	s_cselect_b32 s15, 0x80, s15
	s_add_i32 s13, s13, s15
	s_cmp_eq_u32 s9, 0xb00
	s_cselect_b32 s12, s13, s12
	s_mov_b32 s14, 0x30000
	s_cmp_eq_u32 s5, 1
	s_cselect_b32 s14, 0x30000, s14
	s_cmp_eq_u32 s5, 2
	s_cselect_b32 s14, 0xb30000, s14
	s_cmp_eq_u32 s5, 3
	s_cselect_b32 s14, 0x10b0000, s14
	s_cmp_eq_u32 s5, 4
	s_cselect_b32 s14, 0x10b0000, s14
	s_cmp_eq_u32 s5, 5
	s_cselect_b32 s14, 0x1bb0000, s14
	s_cmp_eq_u32 s5, 6
	s_cselect_b32 s14, 0x2130000, s14
	s_cmp_eq_u32 s5, 7
	s_cselect_b32 s14, 0x28f0000, s14
	s_cmp_eq_u32 s5, 6
	s_cselect_b32 s15, 1, 0
	s_cmp_ge_u32 s7, 24
	s_cselect_b32 s13, s15, 0
	s_cmp_eq_u32 s13, 1
	s_cselect_b32 s14, 0x2430000, s14
	s_cselect_b32 s13, 0x600, 0
	s_sub_i32 s12, s12, s13
	s_mul_i32 s12, s12, s10
	s_lshl_b32 s13, s8, 6
	s_add_i32 s12, s12, s13
	s_lshl_b32 s12, s12, 1
	s_add_u32 s12, s12, s14
	s_add_u32 s20, s30, s12
	s_addc_u32 s21, s31, 0
	v_mul_u32_u24_e32 v71, s10, v66
	v_add_lshl_u32 v71, v71, v67, 1
	ds_read_b32 v104, v69
	ds_read_b32 v105, v69 offset:260
	ds_read_b32 v106, v69 offset:520
	ds_read_b32 v107, v69 offset:780
	ds_read_b32 v108, v69 offset:1040
	ds_read_b32 v109, v69 offset:1300
	ds_read_b32 v110, v69 offset:1560
	ds_read_b32 v111, v69 offset:1820
	s_waitcnt lgkmcnt(0)
	v_cvt_pk_bf16_f32 v116, v104, v105
	v_cvt_pk_bf16_f32 v117, v106, v107
	v_cvt_pk_bf16_f32 v118, v108, v109
	v_cvt_pk_bf16_f32 v119, v110, v111
	global_store_dwordx4 v71, v[116:119], s[20:21]
	s_barrier
	s_add_i32 s4, s2, 0x1300
	s_mov_b32 s5, 0
	s_cmp_ge_u32 s4, 0x2c0
	s_addc_u32 s5, s5, 0
	s_cmp_ge_u32 s4, 0x580
	s_addc_u32 s5, s5, 0
	s_cmp_ge_u32 s4, 0x840
	s_addc_u32 s5, s5, 0
	s_cmp_ge_u32 s4, 0xb00
	s_addc_u32 s5, s5, 0
	s_cmp_ge_u32 s4, 0xdc0
	s_addc_u32 s5, s5, 0
	s_cmp_ge_u32 s4, 0x1080
	s_addc_u32 s5, s5, 0
	s_cmp_ge_u32 s4, 0x13c0
	s_addc_u32 s5, s5, 0
	s_mul_i32 s12, s5, 0x2c0
	s_cmp_eq_u32 s5, 7
	s_cselect_b32 s13, 0x80, 0
	s_add_i32 s12, s12, s13
	s_sub_i32 s6, s4, s12
	s_cmp_eq_u32 s5, 2
	s_cselect_b32 s14, 1, 0
	s_cmp_eq_u32 s5, 5
	s_cselect_b32 s14, 1, s14
	s_mul_i32 s12, s6, 0x5d2
	s_lshr_b32 s12, s12, 16
	s_mul_i32 s15, s12, 44
	s_sub_i32 s15, s6, s15
	s_lshr_b32 s13, s6, 4
	s_and_b32 s8, s6, 15
	s_cmp_eq_u32 s14, 1
	s_cselect_b32 s7, s12, s13
	s_cselect_b32 s8, s15, s8
	s_movk_i32 s10, 0x400
	s_cselect_b32 s10, 0xb00, s10
	s_movk_i32 s9, 0xb00
	s_cselect_b32 s9, 0x400, s9
	s_cmp_eq_u32 s5, 7
	s_cselect_b32 s9, 0x400, s9
	s_cmp_eq_u32 s5, 6
	s_cselect_b32 s9, 0xd00, s9
	s_lshl_b32 s12, s5, 3
	s_lshr_b64 s[12:13], s[22:23], s12
	s_and_b32 s12, s12, 0xff
	s_add_i32 s13, s12, 1
	v_readlane_b32 s16, v241, s12
	v_readlane_b32 s17, v241, s13
	v_mul_u32_u24_e32 v70, s9, v65
	s_mul_i32 s14, s8, s9
	s_add_i32 s14, s14, s7
	s_lshl_b32 s14, s14, 8
	v_add_lshl_u32 v70, v70, v64, 2
	s_add_u32 s18, s16, s14
	s_addc_u32 s19, s17, 0
	s_lshl_b32 s15, s9, 5
	global_load_dword v96, v70, s[18:19]
	s_add_u32 s18, s18, s15
	s_addc_u32 s19, s19, 0
	global_load_dword v97, v70, s[18:19]
	s_add_u32 s18, s18, s15
	s_addc_u32 s19, s19, 0
	global_load_dword v98, v70, s[18:19]
	s_add_u32 s18, s18, s15
	s_addc_u32 s19, s19, 0
	global_load_dword v99, v70, s[18:19]
	s_add_u32 s18, s18, s15
	s_addc_u32 s19, s19, 0
	global_load_dword v100, v70, s[18:19]
	s_add_u32 s18, s18, s15
	s_addc_u32 s19, s19, 0
	global_load_dword v101, v70, s[18:19]
	s_add_u32 s18, s18, s15
	s_addc_u32 s19, s19, 0
	global_load_dword v102, v70, s[18:19]
	s_add_u32 s18, s18, s15
	s_addc_u32 s19, s19, 0
	global_load_dword v103, v70, s[18:19]
	s_waitcnt vmcnt(27)
	ds_write_b32 v68, v72
	ds_write_b32 v68, v73 offset:2080
	ds_write_b32 v68, v74 offset:4160
	ds_write_b32 v68, v75 offset:6240
	ds_write_b32 v68, v76 offset:8320
	ds_write_b32 v68, v77 offset:10400
	ds_write_b32 v68, v78 offset:12480
	ds_write_b32 v68, v79 offset:14560
	s_waitcnt lgkmcnt(0)
	s_barrier
	s_add_i32 s4, s2, 0x1000
	s_mov_b32 s5, 0
	s_cmp_ge_u32 s4, 0x2c0
	s_addc_u32 s5, s5, 0
	s_cmp_ge_u32 s4, 0x580
	s_addc_u32 s5, s5, 0
	s_cmp_ge_u32 s4, 0x840
	s_addc_u32 s5, s5, 0
	s_cmp_ge_u32 s4, 0xb00
	s_addc_u32 s5, s5, 0
	s_cmp_ge_u32 s4, 0xdc0
	s_addc_u32 s5, s5, 0
	s_cmp_ge_u32 s4, 0x1080
	s_addc_u32 s5, s5, 0
	s_cmp_ge_u32 s4, 0x13c0
	s_addc_u32 s5, s5, 0
	s_mul_i32 s12, s5, 0x2c0
	s_cmp_eq_u32 s5, 7
	s_cselect_b32 s13, 0x80, 0
	s_add_i32 s12, s12, s13
	s_sub_i32 s6, s4, s12
	s_cmp_eq_u32 s5, 2
	s_cselect_b32 s14, 1, 0
	s_cmp_eq_u32 s5, 5
	s_cselect_b32 s14, 1, s14
	s_mul_i32 s12, s6, 0x5d2
	s_lshr_b32 s12, s12, 16
	s_mul_i32 s15, s12, 44
	s_sub_i32 s15, s6, s15
	s_lshr_b32 s13, s6, 4
	s_and_b32 s8, s6, 15
	s_cmp_eq_u32 s14, 1
	s_cselect_b32 s7, s12, s13
	s_cselect_b32 s8, s15, s8
	s_movk_i32 s10, 0x400
	s_cselect_b32 s10, 0xb00, s10
	s_movk_i32 s9, 0xb00
	s_cselect_b32 s9, 0x400, s9
	s_cmp_eq_u32 s5, 7
	s_cselect_b32 s9, 0x400, s9
	s_cmp_eq_u32 s5, 6
	s_cselect_b32 s9, 0xd00, s9
	s_lshl_b32 s12, s7, 6
	s_lshr_b32 s13, s7, 1
	s_lshl_b32 s13, s13, 8
	s_and_b32 s15, s7, 1
	s_lshl_b32 s15, s15, 6
	s_add_i32 s13, s13, s15
	s_and_b32 s15, s5, 1
	s_cmp_eq_u32 s5, 1
	s_cselect_b32 s15, 0x80, 0
	s_cmp_eq_u32 s5, 4
	s_cselect_b32 s15, 0x80, s15
	s_add_i32 s13, s13, s15
	s_cmp_eq_u32 s9, 0xb00
	s_cselect_b32 s12, s13, s12
	s_mov_b32 s14, 0x30000
	s_cmp_eq_u32 s5, 1
	s_cselect_b32 s14, 0x30000, s14
	s_cmp_eq_u32 s5, 2
	s_cselect_b32 s14, 0xb30000, s14
	s_cmp_eq_u32 s5, 3
	s_cselect_b32 s14, 0x10b0000, s14
	s_cmp_eq_u32 s5, 4
	s_cselect_b32 s14, 0x10b0000, s14
	s_cmp_eq_u32 s5, 5
	s_cselect_b32 s14, 0x1bb0000, s14
	s_cmp_eq_u32 s5, 6
	s_cselect_b32 s14, 0x2130000, s14
	s_cmp_eq_u32 s5, 7
	s_cselect_b32 s14, 0x28f0000, s14
	s_cmp_eq_u32 s5, 6
	s_cselect_b32 s15, 1, 0
	s_cmp_ge_u32 s7, 24
	s_cselect_b32 s13, s15, 0
	s_cmp_eq_u32 s13, 1
	s_cselect_b32 s14, 0x2430000, s14
	s_cselect_b32 s13, 0x600, 0
	s_sub_i32 s12, s12, s13
	s_mul_i32 s12, s12, s10
	s_lshl_b32 s13, s8, 6
	s_add_i32 s12, s12, s13
	s_lshl_b32 s12, s12, 1
	s_add_u32 s12, s12, s14
	s_add_u32 s20, s30, s12
	s_addc_u32 s21, s31, 0
	v_mul_u32_u24_e32 v71, s10, v66
	v_add_lshl_u32 v71, v71, v67, 1
	ds_read_b32 v104, v69
	ds_read_b32 v105, v69 offset:260
	ds_read_b32 v106, v69 offset:520
	ds_read_b32 v107, v69 offset:780
	ds_read_b32 v108, v69 offset:1040
	ds_read_b32 v109, v69 offset:1300
	ds_read_b32 v110, v69 offset:1560
	ds_read_b32 v111, v69 offset:1820
	s_waitcnt lgkmcnt(0)
	v_cvt_pk_bf16_f32 v112, v104, v105
	v_cvt_pk_bf16_f32 v113, v106, v107
	v_cvt_pk_bf16_f32 v114, v108, v109
	v_cvt_pk_bf16_f32 v115, v110, v111
	global_store_dwordx4 v71, v[112:115], s[20:21]
	s_barrier
	s_cmpk_gt_u32 s2, 0xbf
	s_cselect_b32 s12, 0, 0x1400
	s_add_i32 s4, s2, s12
	s_mov_b32 s5, 0
	s_cmp_ge_u32 s4, 0x2c0
	s_addc_u32 s5, s5, 0
	s_cmp_ge_u32 s4, 0x580
	s_addc_u32 s5, s5, 0
	s_cmp_ge_u32 s4, 0x840
	s_addc_u32 s5, s5, 0
	s_cmp_ge_u32 s4, 0xb00
	s_addc_u32 s5, s5, 0
	s_cmp_ge_u32 s4, 0xdc0
	s_addc_u32 s5, s5, 0
	s_cmp_ge_u32 s4, 0x1080
	s_addc_u32 s5, s5, 0
	s_cmp_ge_u32 s4, 0x13c0
	s_addc_u32 s5, s5, 0
	s_mul_i32 s12, s5, 0x2c0
	s_cmp_eq_u32 s5, 7
	s_cselect_b32 s13, 0x80, 0
	s_add_i32 s12, s12, s13
	s_sub_i32 s6, s4, s12
	s_cmp_eq_u32 s5, 2
	s_cselect_b32 s14, 1, 0
	s_cmp_eq_u32 s5, 5
	s_cselect_b32 s14, 1, s14
	s_mul_i32 s12, s6, 0x5d2
	s_lshr_b32 s12, s12, 16
	s_mul_i32 s15, s12, 44
	s_sub_i32 s15, s6, s15
	s_lshr_b32 s13, s6, 4
	s_and_b32 s8, s6, 15
	s_cmp_eq_u32 s14, 1
	s_cselect_b32 s7, s12, s13
	s_cselect_b32 s8, s15, s8
	s_movk_i32 s10, 0x400
	s_cselect_b32 s10, 0xb00, s10
	s_movk_i32 s9, 0xb00
	s_cselect_b32 s9, 0x400, s9
	s_cmp_eq_u32 s5, 7
	s_cselect_b32 s9, 0x400, s9
	s_cmp_eq_u32 s5, 6
	s_cselect_b32 s9, 0xd00, s9
	s_lshl_b32 s12, s5, 3
	s_lshr_b64 s[12:13], s[22:23], s12
	s_and_b32 s12, s12, 0xff
	s_add_i32 s13, s12, 1
	v_readlane_b32 s16, v241, s12
	v_readlane_b32 s17, v241, s13
	v_mul_u32_u24_e32 v70, s9, v65
	s_mul_i32 s14, s8, s9
	s_add_i32 s14, s14, s7
	s_lshl_b32 s14, s14, 8
	v_add_lshl_u32 v70, v70, v64, 2
	s_add_u32 s18, s16, s14
	s_addc_u32 s19, s17, 0
	s_lshl_b32 s15, s9, 5
	global_load_dword v72, v70, s[18:19]
	s_add_u32 s18, s18, s15
	s_addc_u32 s19, s19, 0
	global_load_dword v73, v70, s[18:19]
	s_add_u32 s18, s18, s15
	s_addc_u32 s19, s19, 0
	global_load_dword v74, v70, s[18:19]
	s_add_u32 s18, s18, s15
	s_addc_u32 s19, s19, 0
	global_load_dword v75, v70, s[18:19]
	s_add_u32 s18, s18, s15
	s_addc_u32 s19, s19, 0
	global_load_dword v76, v70, s[18:19]
	s_add_u32 s18, s18, s15
	s_addc_u32 s19, s19, 0
	global_load_dword v77, v70, s[18:19]
	s_add_u32 s18, s18, s15
	s_addc_u32 s19, s19, 0
	global_load_dword v78, v70, s[18:19]
	s_add_u32 s18, s18, s15
	s_addc_u32 s19, s19, 0
	global_load_dword v79, v70, s[18:19]
	s_waitcnt vmcnt(27)
	ds_write_b32 v68, v80
	ds_write_b32 v68, v81 offset:2080
	ds_write_b32 v68, v82 offset:4160
	ds_write_b32 v68, v83 offset:6240
	ds_write_b32 v68, v84 offset:8320
	ds_write_b32 v68, v85 offset:10400
	ds_write_b32 v68, v86 offset:12480
	ds_write_b32 v68, v87 offset:14560
	s_waitcnt lgkmcnt(0)
	s_barrier
	s_add_i32 s4, s2, 0x1100
	s_mov_b32 s5, 0
	s_cmp_ge_u32 s4, 0x2c0
	s_addc_u32 s5, s5, 0
	s_cmp_ge_u32 s4, 0x580
	s_addc_u32 s5, s5, 0
	s_cmp_ge_u32 s4, 0x840
	s_addc_u32 s5, s5, 0
	s_cmp_ge_u32 s4, 0xb00
	s_addc_u32 s5, s5, 0
	s_cmp_ge_u32 s4, 0xdc0
	s_addc_u32 s5, s5, 0
	s_cmp_ge_u32 s4, 0x1080
	s_addc_u32 s5, s5, 0
	s_cmp_ge_u32 s4, 0x13c0
	s_addc_u32 s5, s5, 0
	s_mul_i32 s12, s5, 0x2c0
	s_cmp_eq_u32 s5, 7
	s_cselect_b32 s13, 0x80, 0
	s_add_i32 s12, s12, s13
	s_sub_i32 s6, s4, s12
	s_cmp_eq_u32 s5, 2
	s_cselect_b32 s14, 1, 0
	s_cmp_eq_u32 s5, 5
	s_cselect_b32 s14, 1, s14
	s_mul_i32 s12, s6, 0x5d2
	s_lshr_b32 s12, s12, 16
	s_mul_i32 s15, s12, 44
	s_sub_i32 s15, s6, s15
	s_lshr_b32 s13, s6, 4
	s_and_b32 s8, s6, 15
	s_cmp_eq_u32 s14, 1
	s_cselect_b32 s7, s12, s13
	s_cselect_b32 s8, s15, s8
	s_movk_i32 s10, 0x400
	s_cselect_b32 s10, 0xb00, s10
	s_movk_i32 s9, 0xb00
	s_cselect_b32 s9, 0x400, s9
	s_cmp_eq_u32 s5, 7
	s_cselect_b32 s9, 0x400, s9
	s_cmp_eq_u32 s5, 6
	s_cselect_b32 s9, 0xd00, s9
	s_lshl_b32 s12, s7, 6
	s_lshr_b32 s13, s7, 1
	s_lshl_b32 s13, s13, 8
	s_and_b32 s15, s7, 1
	s_lshl_b32 s15, s15, 6
	s_add_i32 s13, s13, s15
	s_and_b32 s15, s5, 1
	s_cmp_eq_u32 s5, 1
	s_cselect_b32 s15, 0x80, 0
	s_cmp_eq_u32 s5, 4
	s_cselect_b32 s15, 0x80, s15
	s_add_i32 s13, s13, s15
	s_cmp_eq_u32 s9, 0xb00
	s_cselect_b32 s12, s13, s12
	s_mov_b32 s14, 0x30000
	s_cmp_eq_u32 s5, 1
	s_cselect_b32 s14, 0x30000, s14
	s_cmp_eq_u32 s5, 2
	s_cselect_b32 s14, 0xb30000, s14
	s_cmp_eq_u32 s5, 3
	s_cselect_b32 s14, 0x10b0000, s14
	s_cmp_eq_u32 s5, 4
	s_cselect_b32 s14, 0x10b0000, s14
	s_cmp_eq_u32 s5, 5
	s_cselect_b32 s14, 0x1bb0000, s14
	s_cmp_eq_u32 s5, 6
	s_cselect_b32 s14, 0x2130000, s14
	s_cmp_eq_u32 s5, 7
	s_cselect_b32 s14, 0x28f0000, s14
	s_cmp_eq_u32 s5, 6
	s_cselect_b32 s15, 1, 0
	s_cmp_ge_u32 s7, 24
	s_cselect_b32 s13, s15, 0
	s_cmp_eq_u32 s13, 1
	s_cselect_b32 s14, 0x2430000, s14
	s_cselect_b32 s13, 0x600, 0
	s_sub_i32 s12, s12, s13
	s_mul_i32 s12, s12, s10
	s_lshl_b32 s13, s8, 6
	s_add_i32 s12, s12, s13
	s_lshl_b32 s12, s12, 1
	s_add_u32 s12, s12, s14
	s_add_u32 s20, s30, s12
	s_addc_u32 s21, s31, 0
	v_mul_u32_u24_e32 v71, s10, v66
	v_add_lshl_u32 v71, v71, v67, 1
	ds_read_b32 v104, v69
	ds_read_b32 v105, v69 offset:260
	ds_read_b32 v106, v69 offset:520
	ds_read_b32 v107, v69 offset:780
	ds_read_b32 v108, v69 offset:1040
	ds_read_b32 v109, v69 offset:1300
	ds_read_b32 v110, v69 offset:1560
	ds_read_b32 v111, v69 offset:1820
	s_waitcnt lgkmcnt(0)
	v_cvt_pk_bf16_f32 v116, v104, v105
	v_cvt_pk_bf16_f32 v117, v106, v107
	v_cvt_pk_bf16_f32 v118, v108, v109
	v_cvt_pk_bf16_f32 v119, v110, v111
	global_store_dwordx4 v71, v[116:119], s[20:21]
	s_barrier
	s_waitcnt vmcnt(19)
	ds_write_b32 v68, v88
	ds_write_b32 v68, v89 offset:2080
	ds_write_b32 v68, v90 offset:4160
	ds_write_b32 v68, v91 offset:6240
	ds_write_b32 v68, v92 offset:8320
	ds_write_b32 v68, v93 offset:10400
	ds_write_b32 v68, v94 offset:12480
	ds_write_b32 v68, v95 offset:14560
	s_waitcnt lgkmcnt(0)
	s_barrier
	s_add_i32 s4, s2, 0x1200
	s_mov_b32 s5, 0
	s_cmp_ge_u32 s4, 0x2c0
	s_addc_u32 s5, s5, 0
	s_cmp_ge_u32 s4, 0x580
	s_addc_u32 s5, s5, 0
	s_cmp_ge_u32 s4, 0x840
	s_addc_u32 s5, s5, 0
	s_cmp_ge_u32 s4, 0xb00
	s_addc_u32 s5, s5, 0
	s_cmp_ge_u32 s4, 0xdc0
	s_addc_u32 s5, s5, 0
	s_cmp_ge_u32 s4, 0x1080
	s_addc_u32 s5, s5, 0
	s_cmp_ge_u32 s4, 0x13c0
	s_addc_u32 s5, s5, 0
	s_mul_i32 s12, s5, 0x2c0
	s_cmp_eq_u32 s5, 7
	s_cselect_b32 s13, 0x80, 0
	s_add_i32 s12, s12, s13
	s_sub_i32 s6, s4, s12
	s_cmp_eq_u32 s5, 2
	s_cselect_b32 s14, 1, 0
	s_cmp_eq_u32 s5, 5
	s_cselect_b32 s14, 1, s14
	s_mul_i32 s12, s6, 0x5d2
	s_lshr_b32 s12, s12, 16
	s_mul_i32 s15, s12, 44
	s_sub_i32 s15, s6, s15
	s_lshr_b32 s13, s6, 4
	s_and_b32 s8, s6, 15
	s_cmp_eq_u32 s14, 1
	s_cselect_b32 s7, s12, s13
	s_cselect_b32 s8, s15, s8
	s_movk_i32 s10, 0x400
	s_cselect_b32 s10, 0xb00, s10
	s_movk_i32 s9, 0xb00
	s_cselect_b32 s9, 0x400, s9
	s_cmp_eq_u32 s5, 7
	s_cselect_b32 s9, 0x400, s9
	s_cmp_eq_u32 s5, 6
	s_cselect_b32 s9, 0xd00, s9
	s_lshl_b32 s12, s7, 6
	s_lshr_b32 s13, s7, 1
	s_lshl_b32 s13, s13, 8
	s_and_b32 s15, s7, 1
	s_lshl_b32 s15, s15, 6
	s_add_i32 s13, s13, s15
	s_and_b32 s15, s5, 1
	s_cmp_eq_u32 s5, 1
	s_cselect_b32 s15, 0x80, 0
	s_cmp_eq_u32 s5, 4
	s_cselect_b32 s15, 0x80, s15
	s_add_i32 s13, s13, s15
	s_cmp_eq_u32 s9, 0xb00
	s_cselect_b32 s12, s13, s12
	s_mov_b32 s14, 0x30000
	s_cmp_eq_u32 s5, 1
	s_cselect_b32 s14, 0x30000, s14
	s_cmp_eq_u32 s5, 2
	s_cselect_b32 s14, 0xb30000, s14
	s_cmp_eq_u32 s5, 3
	s_cselect_b32 s14, 0x10b0000, s14
	s_cmp_eq_u32 s5, 4
	s_cselect_b32 s14, 0x10b0000, s14
	s_cmp_eq_u32 s5, 5
	s_cselect_b32 s14, 0x1bb0000, s14
	s_cmp_eq_u32 s5, 6
	s_cselect_b32 s14, 0x2130000, s14
	s_cmp_eq_u32 s5, 7
	s_cselect_b32 s14, 0x28f0000, s14
	s_cmp_eq_u32 s5, 6
	s_cselect_b32 s15, 1, 0
	s_cmp_ge_u32 s7, 24
	s_cselect_b32 s13, s15, 0
	s_cmp_eq_u32 s13, 1
	s_cselect_b32 s14, 0x2430000, s14
	s_cselect_b32 s13, 0x600, 0
	s_sub_i32 s12, s12, s13
	s_mul_i32 s12, s12, s10
	s_lshl_b32 s13, s8, 6
	s_add_i32 s12, s12, s13
	s_lshl_b32 s12, s12, 1
	s_add_u32 s12, s12, s14
	s_add_u32 s20, s30, s12
	s_addc_u32 s21, s31, 0
	v_mul_u32_u24_e32 v71, s10, v66
	v_add_lshl_u32 v71, v71, v67, 1
	ds_read_b32 v104, v69
	ds_read_b32 v105, v69 offset:260
	ds_read_b32 v106, v69 offset:520
	ds_read_b32 v107, v69 offset:780
	ds_read_b32 v108, v69 offset:1040
	ds_read_b32 v109, v69 offset:1300
	ds_read_b32 v110, v69 offset:1560
	ds_read_b32 v111, v69 offset:1820
	s_waitcnt lgkmcnt(0)
	v_cvt_pk_bf16_f32 v112, v104, v105
	v_cvt_pk_bf16_f32 v113, v106, v107
	v_cvt_pk_bf16_f32 v114, v108, v109
	v_cvt_pk_bf16_f32 v115, v110, v111
	global_store_dwordx4 v71, v[112:115], s[20:21]
	s_barrier
	s_waitcnt vmcnt(11)
	ds_write_b32 v68, v96
	ds_write_b32 v68, v97 offset:2080
	ds_write_b32 v68, v98 offset:4160
	ds_write_b32 v68, v99 offset:6240
	ds_write_b32 v68, v100 offset:8320
	ds_write_b32 v68, v101 offset:10400
	ds_write_b32 v68, v102 offset:12480
	ds_write_b32 v68, v103 offset:14560
	s_waitcnt lgkmcnt(0)
	s_barrier
	s_add_i32 s4, s2, 0x1300
	s_mov_b32 s5, 0
	s_cmp_ge_u32 s4, 0x2c0
	s_addc_u32 s5, s5, 0
	s_cmp_ge_u32 s4, 0x580
	s_addc_u32 s5, s5, 0
	s_cmp_ge_u32 s4, 0x840
	s_addc_u32 s5, s5, 0
	s_cmp_ge_u32 s4, 0xb00
	s_addc_u32 s5, s5, 0
	s_cmp_ge_u32 s4, 0xdc0
	s_addc_u32 s5, s5, 0
	s_cmp_ge_u32 s4, 0x1080
	s_addc_u32 s5, s5, 0
	s_cmp_ge_u32 s4, 0x13c0
	s_addc_u32 s5, s5, 0
	s_mul_i32 s12, s5, 0x2c0
	s_cmp_eq_u32 s5, 7
	s_cselect_b32 s13, 0x80, 0
	s_add_i32 s12, s12, s13
	s_sub_i32 s6, s4, s12
	s_cmp_eq_u32 s5, 2
	s_cselect_b32 s14, 1, 0
	s_cmp_eq_u32 s5, 5
	s_cselect_b32 s14, 1, s14
	s_mul_i32 s12, s6, 0x5d2
	s_lshr_b32 s12, s12, 16
	s_mul_i32 s15, s12, 44
	s_sub_i32 s15, s6, s15
	s_lshr_b32 s13, s6, 4
	s_and_b32 s8, s6, 15
	s_cmp_eq_u32 s14, 1
	s_cselect_b32 s7, s12, s13
	s_cselect_b32 s8, s15, s8
	s_movk_i32 s10, 0x400
	s_cselect_b32 s10, 0xb00, s10
	s_movk_i32 s9, 0xb00
	s_cselect_b32 s9, 0x400, s9
	s_cmp_eq_u32 s5, 7
	s_cselect_b32 s9, 0x400, s9
	s_cmp_eq_u32 s5, 6
	s_cselect_b32 s9, 0xd00, s9
	s_lshl_b32 s12, s7, 6
	s_lshr_b32 s13, s7, 1
	s_lshl_b32 s13, s13, 8
	s_and_b32 s15, s7, 1
	s_lshl_b32 s15, s15, 6
	s_add_i32 s13, s13, s15
	s_and_b32 s15, s5, 1
	s_cmp_eq_u32 s5, 1
	s_cselect_b32 s15, 0x80, 0
	s_cmp_eq_u32 s5, 4
	s_cselect_b32 s15, 0x80, s15
	s_add_i32 s13, s13, s15
	s_cmp_eq_u32 s9, 0xb00
	s_cselect_b32 s12, s13, s12
	s_mov_b32 s14, 0x30000
	s_cmp_eq_u32 s5, 1
	s_cselect_b32 s14, 0x30000, s14
	s_cmp_eq_u32 s5, 2
	s_cselect_b32 s14, 0xb30000, s14
	s_cmp_eq_u32 s5, 3
	s_cselect_b32 s14, 0x10b0000, s14
	s_cmp_eq_u32 s5, 4
	s_cselect_b32 s14, 0x10b0000, s14
	s_cmp_eq_u32 s5, 5
	s_cselect_b32 s14, 0x1bb0000, s14
	s_cmp_eq_u32 s5, 6
	s_cselect_b32 s14, 0x2130000, s14
	s_cmp_eq_u32 s5, 7
	s_cselect_b32 s14, 0x28f0000, s14
	s_cmp_eq_u32 s5, 6
	s_cselect_b32 s15, 1, 0
	s_cmp_ge_u32 s7, 24
	s_cselect_b32 s13, s15, 0
	s_cmp_eq_u32 s13, 1
	s_cselect_b32 s14, 0x2430000, s14
	s_cselect_b32 s13, 0x600, 0
	s_sub_i32 s12, s12, s13
	s_mul_i32 s12, s12, s10
	s_lshl_b32 s13, s8, 6
	s_add_i32 s12, s12, s13
	s_lshl_b32 s12, s12, 1
	s_add_u32 s12, s12, s14
	s_add_u32 s20, s30, s12
	s_addc_u32 s21, s31, 0
	v_mul_u32_u24_e32 v71, s10, v66
	v_add_lshl_u32 v71, v71, v67, 1
	ds_read_b32 v104, v69
	ds_read_b32 v105, v69 offset:260
	ds_read_b32 v106, v69 offset:520
	ds_read_b32 v107, v69 offset:780
	ds_read_b32 v108, v69 offset:1040
	ds_read_b32 v109, v69 offset:1300
	ds_read_b32 v110, v69 offset:1560
	ds_read_b32 v111, v69 offset:1820
	s_waitcnt lgkmcnt(0)
	v_cvt_pk_bf16_f32 v116, v104, v105
	v_cvt_pk_bf16_f32 v117, v106, v107
	v_cvt_pk_bf16_f32 v118, v108, v109
	v_cvt_pk_bf16_f32 v119, v110, v111
	global_store_dwordx4 v71, v[116:119], s[20:21]
	s_barrier
	s_cmpk_gt_u32 s2, 0xbf
	s_cbranch_scc1 .Lp0tr_done
	s_waitcnt vmcnt(3)
	ds_write_b32 v68, v72
	ds_write_b32 v68, v73 offset:2080
	ds_write_b32 v68, v74 offset:4160
	ds_write_b32 v68, v75 offset:6240
	ds_write_b32 v68, v76 offset:8320
	ds_write_b32 v68, v77 offset:10400
	ds_write_b32 v68, v78 offset:12480
	ds_write_b32 v68, v79 offset:14560
	s_waitcnt lgkmcnt(0)
	s_barrier
	s_add_i32 s4, s2, 0x1400
	s_mov_b32 s5, 0
	s_cmp_ge_u32 s4, 0x2c0
	s_addc_u32 s5, s5, 0
	s_cmp_ge_u32 s4, 0x580
	s_addc_u32 s5, s5, 0
	s_cmp_ge_u32 s4, 0x840
	s_addc_u32 s5, s5, 0
	s_cmp_ge_u32 s4, 0xb00
	s_addc_u32 s5, s5, 0
	s_cmp_ge_u32 s4, 0xdc0
	s_addc_u32 s5, s5, 0
	s_cmp_ge_u32 s4, 0x1080
	s_addc_u32 s5, s5, 0
	s_cmp_ge_u32 s4, 0x13c0
	s_addc_u32 s5, s5, 0
	s_mul_i32 s12, s5, 0x2c0
	s_cmp_eq_u32 s5, 7
	s_cselect_b32 s13, 0x80, 0
	s_add_i32 s12, s12, s13
	s_sub_i32 s6, s4, s12
	s_cmp_eq_u32 s5, 2
	s_cselect_b32 s14, 1, 0
	s_cmp_eq_u32 s5, 5
	s_cselect_b32 s14, 1, s14
	s_mul_i32 s12, s6, 0x5d2
	s_lshr_b32 s12, s12, 16
	s_mul_i32 s15, s12, 44
	s_sub_i32 s15, s6, s15
	s_lshr_b32 s13, s6, 4
	s_and_b32 s8, s6, 15
	s_cmp_eq_u32 s14, 1
	s_cselect_b32 s7, s12, s13
	s_cselect_b32 s8, s15, s8
	s_movk_i32 s10, 0x400
	s_cselect_b32 s10, 0xb00, s10
	s_movk_i32 s9, 0xb00
	s_cselect_b32 s9, 0x400, s9
	s_cmp_eq_u32 s5, 7
	s_cselect_b32 s9, 0x400, s9
	s_cmp_eq_u32 s5, 6
	s_cselect_b32 s9, 0xd00, s9
	s_lshl_b32 s12, s7, 6
	s_lshr_b32 s13, s7, 1
	s_lshl_b32 s13, s13, 8
	s_and_b32 s15, s7, 1
	s_lshl_b32 s15, s15, 6
	s_add_i32 s13, s13, s15
	s_and_b32 s15, s5, 1
	s_cmp_eq_u32 s5, 1
	s_cselect_b32 s15, 0x80, 0
	s_cmp_eq_u32 s5, 4
	s_cselect_b32 s15, 0x80, s15
	s_add_i32 s13, s13, s15
	s_cmp_eq_u32 s9, 0xb00
	s_cselect_b32 s12, s13, s12
	s_mov_b32 s14, 0x30000
	s_cmp_eq_u32 s5, 1
	s_cselect_b32 s14, 0x30000, s14
	s_cmp_eq_u32 s5, 2
	s_cselect_b32 s14, 0xb30000, s14
	s_cmp_eq_u32 s5, 3
	s_cselect_b32 s14, 0x10b0000, s14
	s_cmp_eq_u32 s5, 4
	s_cselect_b32 s14, 0x10b0000, s14
	s_cmp_eq_u32 s5, 5
	s_cselect_b32 s14, 0x1bb0000, s14
	s_cmp_eq_u32 s5, 6
	s_cselect_b32 s14, 0x2130000, s14
	s_cmp_eq_u32 s5, 7
	s_cselect_b32 s14, 0x28f0000, s14
	s_cmp_eq_u32 s5, 6
	s_cselect_b32 s15, 1, 0
	s_cmp_ge_u32 s7, 24
	s_cselect_b32 s13, s15, 0
	s_cmp_eq_u32 s13, 1
	s_cselect_b32 s14, 0x2430000, s14
	s_cselect_b32 s13, 0x600, 0
	s_sub_i32 s12, s12, s13
	s_mul_i32 s12, s12, s10
	s_lshl_b32 s13, s8, 6
	s_add_i32 s12, s12, s13
	s_lshl_b32 s12, s12, 1
	s_add_u32 s12, s12, s14
	s_add_u32 s20, s30, s12
	s_addc_u32 s21, s31, 0
	v_mul_u32_u24_e32 v71, s10, v66
	v_add_lshl_u32 v71, v71, v67, 1
	ds_read_b32 v104, v69
	ds_read_b32 v105, v69 offset:260
	ds_read_b32 v106, v69 offset:520
	ds_read_b32 v107, v69 offset:780
	ds_read_b32 v108, v69 offset:1040
	ds_read_b32 v109, v69 offset:1300
	ds_read_b32 v110, v69 offset:1560
	ds_read_b32 v111, v69 offset:1820
	s_waitcnt lgkmcnt(0)
	v_cvt_pk_bf16_f32 v112, v104, v105
	v_cvt_pk_bf16_f32 v113, v106, v107
	v_cvt_pk_bf16_f32 v114, v108, v109
	v_cvt_pk_bf16_f32 v115, v110, v111
	global_store_dwordx4 v71, v[112:115], s[20:21]
	s_barrier
.Lp0tr_done:
.LBB0_346:
	v_add_u32_e32 v4, s80, v182
	s_mov_b32 s0, 0xa0000
	v_cmp_gt_i32_e32 vcc, s0, v4
	s_and_saveexec_b64 s[0:1], vcc
	s_cbranch_execz .LBB0_363
	s_mov_b64 s[28:29], 0
	s_branch .LBB0_350

.LBB0_388:
	s_cmp_lt_u32 s6, 0x40001
	s_mov_b64 s[28:29], 0
	s_cselect_b64 s[36:37], -1, 0
	s_and_b64 vcc, exec, s[36:37]
	s_cbranch_vccz .LBB0_381
	s_branch .LBB0_387
.LBB0_391:
	s_andn2_b64 vcc, exec, s[28:29]
	s_cbranch_vccz .LBB0_395
	s_mov_b64 s[34:35], exec
	v_mbcnt_lo_u32_b32 v16, s34, 0
	v_mbcnt_hi_u32_b32 v16, s35, v16
	v_cmp_eq_u32_e32 vcc, 0, v16
	s_and_saveexec_b64 s[28:29], vcc
	s_cbranch_execz .LBB0_394
	s_bcnt1_i32_b64 s5, s[34:35]
	v_readlane_b32 s6, v242, 2
	v_mov_b32_e32 v16, s5
	v_readlane_b32 s7, v242, 3
	s_nop 4
	global_atomic_add v180, v16, s[6:7]
